# cross-lane reductions in GEMM epilogues / merge / x-convert: ds_bpermute LDS round trips replaced by DPP and v_permlane16/32_swap (same sums)
# baseline (speedup 1.0000x reference)
;     __device__ __forceinline__ void operator()(const f32x4 (&acc)[2][2][4][2], const Unit& u, int wr, int wc, int fr, int fq, const float (&pre)[8]) const {
;     ...
;                     for (int bj = 0; bj < 2; ++bj) { const f32x4 a = acc[ai][bj][m][0] * rs, b = acc[ai][bj][m][1] * rs;
;                         float ss = ((a[0] * a[0] + a[1] * a[1]) + (a[2] * a[2] + a[3] * a[3])) + ((b[0] * b[0] + b[1] * b[1]) + (b[2] * b[2] + b[3] * b[3]));
;                         ss += __shfl_xor(ss, 16); ss += __shfl_xor(ss, 32);
;                         if (fq == 0) xl[((ai * HALF + wr * 64 + m * 16 + fr) * 2 + bj) * 4 + wc] = ss; } }
.LBB0_42:
	v_cndmask_b32_e64 v146, 0, 1, s[0:1]
	v_cmp_ne_u32_e64 s[12:13], 1, v146
	s_andn2_b64 vcc, exec, s[0:1]
	s_cbranch_vccnz .LBB0_46
	v_and_b32_e32 v147, 64, v222
	v_xor_b32_e32 v146, 16, v222
	v_add_u32_e32 v147, 64, v147
	v_cmp_lt_i32_e32 vcc, v146, v147
	v_xor_b32_e32 v148, 32, v222
	s_nop 0
	v_cndmask_b32_e32 v146, v222, v146, vcc
	v_lshlrev_b32_e32 v146, 2, v146
	v_mov_b32_e32 v146, v237
	s_nop 1
	v_permlane16_swap_b32_e32 v146, v237
	v_cmp_lt_i32_e32 vcc, v148, v147
	s_waitcnt lgkmcnt(0)
	v_add_f32_e32 v146, v237, v146
	v_cndmask_b32_e32 v147, v222, v148, vcc
	v_lshlrev_b32_e32 v147, 2, v147
	v_mov_b32_e32 v147, v146
	s_nop 1
	v_permlane32_swap_b32_e32 v147, v146
	s_and_saveexec_b64 s[34:35], s[6:7]
	s_cbranch_execz .LBB0_45
	s_waitcnt lgkmcnt(0)
	v_add_f32_e32 v146, v146, v147
	ds_write_b32 v228, v146

;     __device__ __forceinline__ void operator()(const f32x4 (&acc)[2][2][4][2], const Unit& u, int wr, int wc, int fr, int fq, const float (&pre)[8]) const {
;     ...
;                     for (int bj = 0; bj < 2; ++bj) { const f32x4 a = acc[ai][bj][m][0] * rs, b = acc[ai][bj][m][1] * rs;
;                         float ss = ((a[0] * a[0] + a[1] * a[1]) + (a[2] * a[2] + a[3] * a[3])) + ((b[0] * b[0] + b[1] * b[1]) + (b[2] * b[2] + b[3] * b[3]));
;                         ss += __shfl_xor(ss, 16); ss += __shfl_xor(ss, 32);
;                         if (fq == 0) xl[((ai * HALF + wr * 64 + m * 16 + fr) * 2 + bj) * 4 + wc] = ss; } }
.LBB0_52:
	s_and_b64 vcc, exec, s[12:13]
	s_cbranch_vccnz .LBB0_56
	v_and_b32_e32 v123, 64, v222
	v_xor_b32_e32 v122, 16, v222
	v_add_u32_e32 v123, 64, v123
	v_cmp_lt_i32_e32 vcc, v122, v123
	v_xor_b32_e32 v124, 32, v222
	s_nop 0
	v_cndmask_b32_e32 v122, v222, v122, vcc
	v_lshlrev_b32_e32 v122, 2, v122
	v_mov_b32_e32 v122, v152
	s_nop 1
	v_permlane16_swap_b32_e32 v122, v152
	v_cmp_lt_i32_e32 vcc, v124, v123
	s_waitcnt lgkmcnt(0)
	v_add_f32_e32 v122, v152, v122
	v_cndmask_b32_e32 v123, v222, v124, vcc
	v_lshlrev_b32_e32 v123, 2, v123
	v_mov_b32_e32 v123, v122
	s_nop 1
	v_permlane32_swap_b32_e32 v123, v122
	s_and_saveexec_b64 s[34:35], s[6:7]
	s_cbranch_execz .LBB0_55
	s_waitcnt lgkmcnt(0)
	v_add_f32_e32 v122, v122, v123
	ds_write_b32 v229, v122

;     __device__ __forceinline__ void operator()(const f32x4 (&acc)[2][2][4][2], const Unit& u, int wr, int wc, int fr, int fq, const float (&pre)[8]) const {
;     ...
;                     for (int bj = 0; bj < 2; ++bj) { const f32x4 a = acc[ai][bj][m][0] * rs, b = acc[ai][bj][m][1] * rs;
;                         float ss = ((a[0] * a[0] + a[1] * a[1]) + (a[2] * a[2] + a[3] * a[3])) + ((b[0] * b[0] + b[1] * b[1]) + (b[2] * b[2] + b[3] * b[3]));
;                         ss += __shfl_xor(ss, 16); ss += __shfl_xor(ss, 32);
;                         if (fq == 0) xl[((ai * HALF + wr * 64 + m * 16 + fr) * 2 + bj) * 4 + wc] = ss; } }
.LBB0_62:
	s_and_b64 vcc, exec, s[12:13]
	s_cbranch_vccnz .LBB0_66
	v_and_b32_e32 v95, 64, v222
	v_xor_b32_e32 v94, 16, v222
	v_add_u32_e32 v95, 64, v95
	v_cmp_lt_i32_e32 vcc, v94, v95
	v_xor_b32_e32 v96, 32, v222
	s_nop 0
	v_cndmask_b32_e32 v94, v222, v94, vcc
	v_lshlrev_b32_e32 v94, 2, v94
	v_mov_b32_e32 v94, v128
	s_nop 1
	v_permlane16_swap_b32_e32 v94, v128
	v_cmp_lt_i32_e32 vcc, v96, v95
	s_waitcnt lgkmcnt(0)
	v_add_f32_e32 v94, v128, v94
	v_cndmask_b32_e32 v95, v222, v96, vcc
	v_lshlrev_b32_e32 v95, 2, v95
	v_mov_b32_e32 v95, v94
	s_nop 1
	v_permlane32_swap_b32_e32 v95, v94
	s_and_saveexec_b64 s[34:35], s[6:7]
	s_cbranch_execz .LBB0_65
	s_waitcnt lgkmcnt(0)
	v_add_f32_e32 v94, v94, v95
	ds_write_b32 v230, v94

;     __device__ __forceinline__ void operator()(const f32x4 (&acc)[2][2][4][2], const Unit& u, int wr, int wc, int fr, int fq, const float (&pre)[8]) const {
;     ...
;                     for (int bj = 0; bj < 2; ++bj) { const f32x4 a = acc[ai][bj][m][0] * rs, b = acc[ai][bj][m][1] * rs;
;                         float ss = ((a[0] * a[0] + a[1] * a[1]) + (a[2] * a[2] + a[3] * a[3])) + ((b[0] * b[0] + b[1] * b[1]) + (b[2] * b[2] + b[3] * b[3]));
;                         ss += __shfl_xor(ss, 16); ss += __shfl_xor(ss, 32);
;                         if (fq == 0) xl[((ai * HALF + wr * 64 + m * 16 + fr) * 2 + bj) * 4 + wc] = ss; } }
.LBB0_72:
	s_and_b64 vcc, exec, s[12:13]
	s_cbranch_vccnz .LBB0_76
	v_and_b32_e32 v71, 64, v222
	v_xor_b32_e32 v70, 16, v222
	v_add_u32_e32 v71, 64, v71
	v_cmp_lt_i32_e32 vcc, v70, v71
	v_xor_b32_e32 v72, 32, v222
	s_nop 0
	v_cndmask_b32_e32 v70, v222, v70, vcc
	v_lshlrev_b32_e32 v70, 2, v70
	v_mov_b32_e32 v70, v100
	s_nop 1
	v_permlane16_swap_b32_e32 v70, v100
	v_cmp_lt_i32_e32 vcc, v72, v71
	s_waitcnt lgkmcnt(0)
	v_add_f32_e32 v70, v100, v70
	v_cndmask_b32_e32 v71, v222, v72, vcc
	v_lshlrev_b32_e32 v71, 2, v71
	v_mov_b32_e32 v71, v70
	s_nop 1
	v_permlane32_swap_b32_e32 v71, v70
	s_and_saveexec_b64 s[34:35], s[6:7]
	s_cbranch_execz .LBB0_75
	s_waitcnt lgkmcnt(0)
	v_add_f32_e32 v70, v70, v71
	ds_write_b32 v231, v70

;     __device__ __forceinline__ void operator()(const f32x4 (&acc)[2][2][4][2], const Unit& u, int wr, int wc, int fr, int fq, const float (&pre)[8]) const {
;     ...
;                     for (int bj = 0; bj < 2; ++bj) { const f32x4 a = acc[ai][bj][m][0] * rs, b = acc[ai][bj][m][1] * rs;
;                         float ss = ((a[0] * a[0] + a[1] * a[1]) + (a[2] * a[2] + a[3] * a[3])) + ((b[0] * b[0] + b[1] * b[1]) + (b[2] * b[2] + b[3] * b[3]));
;                         ss += __shfl_xor(ss, 16); ss += __shfl_xor(ss, 32);
;                         if (fq == 0) xl[((ai * HALF + wr * 64 + m * 16 + fr) * 2 + bj) * 4 + wc] = ss; } }
.LBB0_82:
	s_and_b64 vcc, exec, s[12:13]
	s_cbranch_vccnz .LBB0_86
	v_and_b32_e32 v51, 64, v222
	v_xor_b32_e32 v50, 16, v222
	v_add_u32_e32 v51, 64, v51
	v_cmp_lt_i32_e32 vcc, v50, v51
	v_xor_b32_e32 v52, 32, v222
	s_nop 0
	v_cndmask_b32_e32 v50, v222, v50, vcc
	v_lshlrev_b32_e32 v50, 2, v50
	v_mov_b32_e32 v50, v76
	s_nop 1
	v_permlane16_swap_b32_e32 v50, v76
	v_cmp_lt_i32_e32 vcc, v52, v51
	s_waitcnt lgkmcnt(0)
	v_add_f32_e32 v50, v76, v50
	v_cndmask_b32_e32 v51, v222, v52, vcc
	v_lshlrev_b32_e32 v51, 2, v51
	v_mov_b32_e32 v51, v50
	s_nop 1
	v_permlane32_swap_b32_e32 v51, v50
	s_and_saveexec_b64 s[34:35], s[6:7]
	s_cbranch_execz .LBB0_85
	s_waitcnt lgkmcnt(0)
	v_add_f32_e32 v50, v50, v51
	ds_write_b32 v232, v50

;     __device__ __forceinline__ void operator()(const f32x4 (&acc)[2][2][4][2], const Unit& u, int wr, int wc, int fr, int fq, const float (&pre)[8]) const {
;     ...
;                     for (int bj = 0; bj < 2; ++bj) { const f32x4 a = acc[ai][bj][m][0] * rs, b = acc[ai][bj][m][1] * rs;
;                         float ss = ((a[0] * a[0] + a[1] * a[1]) + (a[2] * a[2] + a[3] * a[3])) + ((b[0] * b[0] + b[1] * b[1]) + (b[2] * b[2] + b[3] * b[3]));
;                         ss += __shfl_xor(ss, 16); ss += __shfl_xor(ss, 32);
;                         if (fq == 0) xl[((ai * HALF + wr * 64 + m * 16 + fr) * 2 + bj) * 4 + wc] = ss; } }
.LBB0_92:
	s_and_b64 vcc, exec, s[12:13]
	s_cbranch_vccnz .LBB0_96
	v_and_b32_e32 v35, 64, v222
	v_xor_b32_e32 v34, 16, v222
	v_add_u32_e32 v35, 64, v35
	v_cmp_lt_i32_e32 vcc, v34, v35
	v_xor_b32_e32 v36, 32, v222
	s_nop 0
	v_cndmask_b32_e32 v34, v222, v34, vcc
	v_lshlrev_b32_e32 v34, 2, v34
	v_mov_b32_e32 v34, v56
	s_nop 1
	v_permlane16_swap_b32_e32 v34, v56
	v_cmp_lt_i32_e32 vcc, v36, v35
	s_waitcnt lgkmcnt(0)
	v_add_f32_e32 v34, v56, v34
	v_cndmask_b32_e32 v35, v222, v36, vcc
	v_lshlrev_b32_e32 v35, 2, v35
	v_mov_b32_e32 v35, v34
	s_nop 1
	v_permlane32_swap_b32_e32 v35, v34
	s_and_saveexec_b64 s[34:35], s[6:7]
	s_cbranch_execz .LBB0_95
	s_waitcnt lgkmcnt(0)
	v_add_f32_e32 v34, v34, v35
	ds_write_b32 v233, v34

;     __device__ __forceinline__ void operator()(const f32x4 (&acc)[2][2][4][2], const Unit& u, int wr, int wc, int fr, int fq, const float (&pre)[8]) const {
;     ...
;                     for (int bj = 0; bj < 2; ++bj) { const f32x4 a = acc[ai][bj][m][0] * rs, b = acc[ai][bj][m][1] * rs;
;                         float ss = ((a[0] * a[0] + a[1] * a[1]) + (a[2] * a[2] + a[3] * a[3])) + ((b[0] * b[0] + b[1] * b[1]) + (b[2] * b[2] + b[3] * b[3]));
;                         ss += __shfl_xor(ss, 16); ss += __shfl_xor(ss, 32);
;                         if (fq == 0) xl[((ai * HALF + wr * 64 + m * 16 + fr) * 2 + bj) * 4 + wc] = ss; } }
.LBB0_102:
	s_and_b64 vcc, exec, s[12:13]
	s_cbranch_vccnz .LBB0_106
	v_and_b32_e32 v19, 64, v222
	v_xor_b32_e32 v18, 16, v222
	v_add_u32_e32 v19, 64, v19
	v_cmp_lt_i32_e32 vcc, v18, v19
	v_xor_b32_e32 v20, 32, v222
	s_nop 0
	v_cndmask_b32_e32 v18, v222, v18, vcc
	v_lshlrev_b32_e32 v18, 2, v18
	v_mov_b32_e32 v18, v40
	s_nop 1
	v_permlane16_swap_b32_e32 v18, v40
	v_cmp_lt_i32_e32 vcc, v20, v19
	s_waitcnt lgkmcnt(0)
	v_add_f32_e32 v18, v40, v18
	v_cndmask_b32_e32 v19, v222, v20, vcc
	v_lshlrev_b32_e32 v19, 2, v19
	v_mov_b32_e32 v19, v18
	s_nop 1
	v_permlane32_swap_b32_e32 v19, v18
	s_and_saveexec_b64 s[34:35], s[6:7]
	s_cbranch_execz .LBB0_105
	s_waitcnt lgkmcnt(0)
	v_add_f32_e32 v18, v18, v19
	ds_write_b32 v234, v18

;     __device__ __forceinline__ void operator()(const f32x4 (&acc)[2][2][4][2], const Unit& u, int wr, int wc, int fr, int fq, const float (&pre)[8]) const {
;     ...
;                     for (int bj = 0; bj < 2; ++bj) { const f32x4 a = acc[ai][bj][m][0] * rs, b = acc[ai][bj][m][1] * rs;
;                         float ss = ((a[0] * a[0] + a[1] * a[1]) + (a[2] * a[2] + a[3] * a[3])) + ((b[0] * b[0] + b[1] * b[1]) + (b[2] * b[2] + b[3] * b[3]));
;                         ss += __shfl_xor(ss, 16); ss += __shfl_xor(ss, 32);
;                         if (fq == 0) xl[((ai * HALF + wr * 64 + m * 16 + fr) * 2 + bj) * 4 + wc] = ss; } }
.LBB0_114:
	v_and_b32_e32 v3, 64, v222
	v_xor_b32_e32 v2, 16, v222
	v_add_u32_e32 v3, 64, v3
	v_cmp_lt_i32_e32 vcc, v2, v3
	v_xor_b32_e32 v4, 32, v222
	s_nop 0
	v_cndmask_b32_e32 v2, v222, v2, vcc
	v_lshlrev_b32_e32 v2, 2, v2
	v_mov_b32_e32 v2, v24
	s_nop 1
	v_permlane16_swap_b32_e32 v2, v24
	v_cmp_lt_i32_e32 vcc, v4, v3
	s_waitcnt lgkmcnt(0)
	v_add_f32_e32 v2, v24, v2
	v_cndmask_b32_e32 v3, v222, v4, vcc
	v_lshlrev_b32_e32 v3, 2, v3
	v_mov_b32_e32 v3, v2
	s_nop 1
	v_permlane32_swap_b32_e32 v3, v2
	s_and_saveexec_b64 s[10:11], s[6:7]
	s_cbranch_execz .LBB0_116
	s_waitcnt lgkmcnt(0)
	v_add_f32_e32 v2, v2, v3
	ds_write_b32 v235, v2

; __device__ __forceinline__ unsigned cvt_pk_bf16(float lo, float hi) { unsigned r; asm volatile("v_cvt_pk_bf16_f32 %0, %1, %2" : "=v"(r) : "v"(lo), "v"(hi)); return r; }
;     __device__ __forceinline__ void operator()(const f32x4 (&acc)[2][2][4][2], const Unit& u, int wr, int wc, int fr, int fq, const float (&)[8]) const {
;     ...
;                 for (int bj = 0; bj < 2; ++bj) bx[ai][m][bj] = *(const u32x4*)(xb + (size_t)(u.pm * BM + ai * HALF + wr * 64 + m * 16 + fr) * ldc + col0 + bj * HALF);
;         asm volatile("" ::: "memory");
; #pragma unroll
;         for (int ai = 0; ai < 2; ++ai)
; #pragma unroll
;             for (int m = 0; m < 4; ++m) { const int rl = ai * HALF + wr * 64 + m * 16 + fr; const size_t off = (size_t)(u.pm * BM + rl) * ldc + col0;
;                 float ss = 0.f;
; #pragma unroll
;                 for (int bj = 0; bj < 2; ++bj) { const u32x4 b = bx[ai][m][bj];
;                     f32x4 o0, o1;
;                     o0[0] = __builtin_bit_cast(float, b.x << 16) + acc[ai][bj][m][0][0]; o0[1] = __builtin_bit_cast(float, b.x & 0xffff0000u) + acc[ai][bj][m][0][1];
;                     o0[2] = __builtin_bit_cast(float, b.y << 16) + acc[ai][bj][m][0][2]; o0[3] = __builtin_bit_cast(float, b.y & 0xffff0000u) + acc[ai][bj][m][0][3];
;                     o1[0] = __builtin_bit_cast(float, b.z << 16) + acc[ai][bj][m][1][0]; o1[1] = __builtin_bit_cast(float, b.z & 0xffff0000u) + acc[ai][bj][m][1][1];
;                     o1[2] = __builtin_bit_cast(float, b.w << 16) + acc[ai][bj][m][1][2]; o1[3] = __builtin_bit_cast(float, b.w & 0xffff0000u) + acc[ai][bj][m][1][3];
;                     if (outf) { *(f32x4*)(outf + off + bj * HALF) = o0; *(f32x4*)(outf + off + bj * HALF + 4) = o1; }
;                     else { ss += ((o0[0] * o0[0] + o0[1] * o0[1]) + (o0[2] * o0[2] + o0[3] * o0[3])) + ((o1[0] * o1[0] + o1[1] * o1[1]) + (o1[2] * o1[2] + o1[3] * o1[3]));
;                         u32x4 w; w.x = cvt_pk_bf16(o0[0], o0[1]); w.y = cvt_pk_bf16(o0[2], o0[3]); w.z = cvt_pk_bf16(o1[0], o1[1]); w.w = cvt_pk_bf16(o1[2], o1[3]); *(u32x4*)(xb + off + bj * HALF) = w; } }
;                 if (rsq_out) { ss += __shfl_xor(ss, 16); ss += __shfl_xor(ss, 32); if (fq == 0) xl[rl * 4 + wc] = ss; } }
.LBB0_181:
	v_lshl_or_b32 v210, s16, 8, v217
	s_lshl_b32 s10, s17, 8
	v_add_u32_e32 v126, s10, v1
	v_ashrrev_i32_e32 v211, 31, v210
	v_lshlrev_b64 v[212:213], 1, v[210:211]
	v_ashrrev_i32_e32 v127, 31, v126
	v_lshl_add_u64 v[128:129], s[12:13], 0, v[212:213]
	v_lshlrev_b64 v[214:215], 12, v[126:127]
	v_lshl_add_u64 v[122:123], v[128:129], 0, v[214:215]
	global_load_dwordx4 v[190:193], v[122:123], off
	global_load_dwordx4 v[186:189], v[122:123], off offset:256
	v_or_b32_e32 v122, 16, v126
	v_ashrrev_i32_e32 v123, 31, v122
	v_lshlrev_b64 v[122:123], 12, v[122:123]
	v_lshl_add_u64 v[122:123], v[128:129], 0, v[122:123]
	global_load_dwordx4 v[182:185], v[122:123], off
	global_load_dwordx4 v[178:181], v[122:123], off offset:256
	v_or_b32_e32 v122, 32, v126
	v_ashrrev_i32_e32 v123, 31, v122
	v_lshlrev_b64 v[122:123], 12, v[122:123]
	v_lshl_add_u64 v[122:123], v[128:129], 0, v[122:123]
	global_load_dwordx4 v[174:177], v[122:123], off
	global_load_dwordx4 v[170:173], v[122:123], off offset:256
	v_or_b32_e32 v122, 48, v126
	v_ashrrev_i32_e32 v123, 31, v122
	v_lshlrev_b64 v[122:123], 12, v[122:123]
	v_lshl_add_u64 v[122:123], v[128:129], 0, v[122:123]
	global_load_dwordx4 v[166:169], v[122:123], off
	global_load_dwordx4 v[162:165], v[122:123], off offset:256
	v_add_u32_e32 v122, 0x80, v126
	v_ashrrev_i32_e32 v123, 31, v122
	v_lshlrev_b64 v[122:123], 12, v[122:123]
	v_lshl_add_u64 v[122:123], v[128:129], 0, v[122:123]
	global_load_dwordx4 v[158:161], v[122:123], off
	global_load_dwordx4 v[154:157], v[122:123], off offset:256
	v_add_u32_e32 v122, 0x90, v126
	v_ashrrev_i32_e32 v123, 31, v122
	v_lshlrev_b64 v[122:123], 12, v[122:123]
	v_lshl_add_u64 v[122:123], v[128:129], 0, v[122:123]
	global_load_dwordx4 v[150:153], v[122:123], off
	global_load_dwordx4 v[138:141], v[122:123], off offset:256
	v_add_u32_e32 v122, 0xa0, v126
	v_add_u32_e32 v126, 0xb0, v126
	v_ashrrev_i32_e32 v123, 31, v122
	v_ashrrev_i32_e32 v127, 31, v126
	v_lshlrev_b64 v[122:123], 12, v[122:123]
	v_lshlrev_b64 v[126:127], 12, v[126:127]
	v_lshl_add_u64 v[122:123], v[128:129], 0, v[122:123]
	v_lshl_add_u64 v[126:127], v[128:129], 0, v[126:127]
	global_load_dwordx4 v[130:133], v[122:123], off
	s_nop 0
	global_load_dwordx4 v[122:125], v[122:123], off offset:256
	s_nop 0
	global_load_dwordx4 v[142:145], v[126:127], off
	s_nop 0
	global_load_dwordx4 v[126:129], v[126:127], off offset:256
	s_waitcnt vmcnt(0)
	v_lshlrev_b32_e32 v198, 16, v190
	v_and_b32_e32 v190, 0xffff0000, v190
	v_add_f32_e32 v147, v147, v190
	v_lshlrev_b32_e32 v190, 16, v191
	v_add_f32_e32 v148, v148, v190
	v_and_b32_e32 v190, 0xffff0000, v191
	v_add_f32_e32 v149, v149, v190
	v_lshlrev_b32_e32 v190, 16, v192
	v_add_f32_e32 v190, v134, v190
	v_and_b32_e32 v134, 0xffff0000, v192
	v_add_f32_e32 v191, v135, v134
	v_lshlrev_b32_e32 v134, 16, v193
	v_add_f32_e32 v192, v136, v134
	v_and_b32_e32 v134, 0xffff0000, v193
	v_add_f32_e32 v146, v146, v198
	v_add_f32_e32 v137, v137, v134
	v_mul_f32_e32 v134, v147, v147
	v_mul_f32_e32 v135, v149, v149
	v_fmac_f32_e32 v134, v146, v146
	v_fmac_f32_e32 v135, v148, v148
	v_add_f32_e32 v134, v134, v135
	v_mul_f32_e32 v135, v191, v191
	v_mul_f32_e32 v136, v137, v137
	v_fmac_f32_e32 v135, v190, v190
	v_fmac_f32_e32 v136, v192, v192
	v_add_f32_e32 v135, v135, v136
	v_add_f32_e32 v193, v134, v135
	v_cvt_pk_bf16_f32 v134, v146, v147
	v_lshl_add_u64 v[146:147], s[12:13], 0, v[214:215]
	v_lshl_add_u64 v[146:147], v[146:147], 0, v[212:213]
	v_cvt_pk_bf16_f32 v135, v148, v149
	v_cvt_pk_bf16_f32 v136, v190, v191
	v_cvt_pk_bf16_f32 v137, v192, v137
	global_store_dwordx4 v[146:147], v[134:137], off
	s_nop 1
	v_lshlrev_b32_e32 v134, 16, v186
	v_add_f32_e32 v118, v118, v134
	v_and_b32_e32 v134, 0xffff0000, v186
	v_add_f32_e32 v119, v119, v134
	v_lshlrev_b32_e32 v134, 16, v187
	v_add_f32_e32 v120, v120, v134
	v_and_b32_e32 v134, 0xffff0000, v187
	v_add_f32_e32 v121, v121, v134
	v_lshlrev_b32_e32 v134, 16, v188
	v_add_f32_e32 v134, v114, v134
	v_and_b32_e32 v114, 0xffff0000, v188
	v_add_f32_e32 v135, v115, v114
	v_lshlrev_b32_e32 v114, 16, v189
	v_add_f32_e32 v136, v116, v114
	v_and_b32_e32 v114, 0xffff0000, v189
	v_add_f32_e32 v117, v117, v114
	v_mul_f32_e32 v114, v119, v119
	v_mul_f32_e32 v115, v121, v121
	v_fmac_f32_e32 v114, v118, v118
	v_fmac_f32_e32 v115, v120, v120
	v_add_f32_e32 v114, v114, v115
	v_mul_f32_e32 v115, v135, v135
	v_mul_f32_e32 v116, v117, v117
	v_fmac_f32_e32 v115, v134, v134
	v_fmac_f32_e32 v116, v136, v136
	v_add_f32_e32 v115, v115, v116
	v_add_f32_e32 v114, v114, v115
	v_add_f32_e32 v137, v193, v114
	v_cvt_pk_bf16_f32 v114, v118, v119
	v_cvt_pk_bf16_f32 v115, v120, v121
	v_cvt_pk_bf16_f32 v116, v134, v135
	v_cvt_pk_bf16_f32 v117, v136, v117
	global_store_dwordx4 v[146:147], v[114:117], off offset:256
	s_nop 1
	v_and_b32_e32 v115, 64, v222
	v_xor_b32_e32 v114, 16, v222
	v_add_u32_e32 v115, 64, v115
	v_cmp_lt_i32_e32 vcc, v114, v115
	v_xor_b32_e32 v117, 32, v222
	s_nop 0
	v_cndmask_b32_e32 v114, v222, v114, vcc
	v_lshlrev_b32_e32 v114, 2, v114
	v_mov_b32_e32 v116, v137
	s_nop 1
	v_permlane16_swap_b32_e32 v116, v137
	v_cmp_lt_i32_e32 vcc, v117, v115
	s_waitcnt lgkmcnt(0)
	v_add_f32_e32 v116, v137, v116
	v_cndmask_b32_e32 v115, v222, v117, vcc
	v_lshlrev_b32_e32 v115, 2, v115
	v_mov_b32_e32 v117, v116
	s_nop 1
	v_permlane32_swap_b32_e32 v117, v116
	s_and_saveexec_b64 s[24:25], s[6:7]
	s_cbranch_execz .LBB0_183
	s_waitcnt lgkmcnt(0)
	v_add_f32_e32 v116, v116, v117
	ds_write_b32 v230, v116
; __device__ __forceinline__ unsigned cvt_pk_bf16(float lo, float hi) { unsigned r; asm volatile("v_cvt_pk_bf16_f32 %0, %1, %2" : "=v"(r) : "v"(lo), "v"(hi)); return r; }
;     __device__ __forceinline__ void operator()(const f32x4 (&acc)[2][2][4][2], const Unit& u, int wr, int wc, int fr, int fq, const float (&)[8]) const {
;     ...
;             for (int m = 0; m < 4; ++m) { const int rl = ai * HALF + wr * 64 + m * 16 + fr; const size_t off = (size_t)(u.pm * BM + rl) * ldc + col0;
;                 float ss = 0.f;
; #pragma unroll
;                 for (int bj = 0; bj < 2; ++bj) { const u32x4 b = bx[ai][m][bj];
;                     f32x4 o0, o1;
;                     o0[0] = __builtin_bit_cast(float, b.x << 16) + acc[ai][bj][m][0][0]; o0[1] = __builtin_bit_cast(float, b.x & 0xffff0000u) + acc[ai][bj][m][0][1];
;                     o0[2] = __builtin_bit_cast(float, b.y << 16) + acc[ai][bj][m][0][2]; o0[3] = __builtin_bit_cast(float, b.y & 0xffff0000u) + acc[ai][bj][m][0][3];
;                     o1[0] = __builtin_bit_cast(float, b.z << 16) + acc[ai][bj][m][1][0]; o1[1] = __builtin_bit_cast(float, b.z & 0xffff0000u) + acc[ai][bj][m][1][1];
;                     o1[2] = __builtin_bit_cast(float, b.w << 16) + acc[ai][bj][m][1][2]; o1[3] = __builtin_bit_cast(float, b.w & 0xffff0000u) + acc[ai][bj][m][1][3];
;                     if (outf) { *(f32x4*)(outf + off + bj * HALF) = o0; *(f32x4*)(outf + off + bj * HALF + 4) = o1; }
;                     else { ss += ((o0[0] * o0[0] + o0[1] * o0[1]) + (o0[2] * o0[2] + o0[3] * o0[3])) + ((o1[0] * o1[0] + o1[1] * o1[1]) + (o1[2] * o1[2] + o1[3] * o1[3]));
;                         u32x4 w; w.x = cvt_pk_bf16(o0[0], o0[1]); w.y = cvt_pk_bf16(o0[2], o0[3]); w.z = cvt_pk_bf16(o1[0], o1[1]); w.w = cvt_pk_bf16(o1[2], o1[3]); *(u32x4*)(xb + off + bj * HALF) = w; } }
;                 if (rsq_out) { ss += __shfl_xor(ss, 16); ss += __shfl_xor(ss, 32); if (fq == 0) xl[rl * 4 + wc] = ss; } }
.LBB0_183:
	s_or_b64 exec, exec, s[24:25]
	v_lshlrev_b32_e32 v118, 16, v182
	v_add_f32_e32 v110, v110, v118
	v_and_b32_e32 v118, 0xffff0000, v182
	v_add_f32_e32 v111, v111, v118
	v_lshlrev_b32_e32 v118, 16, v183
	v_add_f32_e32 v112, v112, v118
	v_and_b32_e32 v118, 0xffff0000, v183
	v_add_f32_e32 v113, v113, v118
	v_lshlrev_b32_e32 v118, 16, v184
	v_add_f32_e32 v118, v106, v118
	v_and_b32_e32 v106, 0xffff0000, v184
	v_add_f32_e32 v119, v107, v106
	v_lshlrev_b32_e32 v106, 16, v185
	v_add_f32_e32 v120, v108, v106
	v_and_b32_e32 v106, 0xffff0000, v185
	v_add_f32_e32 v109, v109, v106
	v_mul_f32_e32 v106, v111, v111
	v_mul_f32_e32 v107, v113, v113
	v_fmac_f32_e32 v106, v110, v110
	v_fmac_f32_e32 v107, v112, v112
	v_add_f32_e32 v106, v106, v107
	v_mul_f32_e32 v107, v119, v119
	v_mul_f32_e32 v108, v109, v109
	v_fmac_f32_e32 v107, v118, v118
	v_fmac_f32_e32 v108, v120, v120
	v_add_f32_e32 v107, v107, v108
	v_add_f32_e32 v121, v106, v107
	v_cvt_pk_bf16_f32 v106, v110, v111
	v_cvt_pk_bf16_f32 v107, v112, v113
	v_lshlrev_b32_e32 v112, 16, v178
	v_add_f32_e32 v102, v102, v112
	v_and_b32_e32 v112, 0xffff0000, v178
	v_add_f32_e32 v103, v103, v112
	v_lshlrev_b32_e32 v112, 16, v179
	v_add_u32_e32 v116, s10, v223
	v_add_f32_e32 v112, v104, v112
	v_and_b32_e32 v104, 0xffff0000, v179
	s_waitcnt lgkmcnt(0)
	v_ashrrev_i32_e32 v117, 31, v116
	v_add_f32_e32 v113, v105, v104
	v_lshlrev_b32_e32 v104, 16, v180
	v_lshlrev_b64 v[110:111], 12, v[116:117]
	v_add_f32_e32 v116, v98, v104
	v_and_b32_e32 v98, 0xffff0000, v180
	v_add_f32_e32 v117, v99, v98
	v_lshlrev_b32_e32 v98, 16, v181
	v_cvt_pk_bf16_f32 v108, v118, v119
	v_add_f32_e32 v118, v100, v98
	v_and_b32_e32 v98, 0xffff0000, v181
	v_add_f32_e32 v119, v101, v98
	v_mul_f32_e32 v98, v103, v103
	v_mul_f32_e32 v99, v113, v113
	v_fmac_f32_e32 v98, v102, v102
	v_fmac_f32_e32 v99, v112, v112
	v_add_f32_e32 v98, v98, v99
	v_mul_f32_e32 v99, v117, v117
	v_mul_f32_e32 v100, v119, v119
	v_fmac_f32_e32 v99, v116, v116
	v_fmac_f32_e32 v100, v118, v118
	v_add_f32_e32 v99, v99, v100
	v_add_f32_e32 v98, v98, v99
	v_add_f32_e32 v101, v121, v98
	v_cvt_pk_bf16_f32 v109, v120, v109
	v_mov_b32_e32 v120, v101
	s_nop 1
	v_permlane16_swap_b32_e32 v120, v101
	v_lshl_add_u64 v[98:99], s[12:13], 0, v[110:111]
	v_lshl_add_u64 v[104:105], v[210:211], 1, v[98:99]
	global_store_dwordx4 v[104:105], v[106:109], off
	v_cvt_pk_bf16_f32 v100, v102, v103
	s_waitcnt lgkmcnt(0)
	v_add_f32_e32 v98, v101, v120
	v_mov_b32_e32 v99, v98
	s_nop 1
	v_permlane32_swap_b32_e32 v99, v98
	v_cvt_pk_bf16_f32 v101, v112, v113
	v_cvt_pk_bf16_f32 v102, v116, v117
	v_cvt_pk_bf16_f32 v103, v118, v119
	global_store_dwordx4 v[104:105], v[100:103], off offset:256
	s_and_saveexec_b64 s[24:25], s[6:7]
	s_cbranch_execz .LBB0_185
	s_waitcnt lgkmcnt(0)
	v_add_f32_e32 v98, v98, v99
	ds_write_b32 v231, v98
.LBB0_185:
	s_or_b64 exec, exec, s[24:25]
	v_lshlrev_b32_e32 v100, 16, v174
	v_add_f32_e32 v94, v94, v100
	v_and_b32_e32 v100, 0xffff0000, v174
	v_add_f32_e32 v95, v95, v100
	v_lshlrev_b32_e32 v100, 16, v175
	v_add_f32_e32 v96, v96, v100
	v_and_b32_e32 v100, 0xffff0000, v175
	v_add_f32_e32 v97, v97, v100
	v_lshlrev_b32_e32 v100, 16, v176
	v_add_f32_e32 v100, v90, v100
	v_and_b32_e32 v90, 0xffff0000, v176
	v_add_f32_e32 v101, v91, v90
	v_lshlrev_b32_e32 v90, 16, v177
	v_add_f32_e32 v102, v92, v90
	v_and_b32_e32 v90, 0xffff0000, v177
	v_add_f32_e32 v93, v93, v90
	v_mul_f32_e32 v90, v95, v95
	v_mul_f32_e32 v91, v97, v97
	v_fmac_f32_e32 v90, v94, v94
	v_fmac_f32_e32 v91, v96, v96
	v_add_f32_e32 v90, v90, v91
	v_mul_f32_e32 v91, v101, v101
	v_mul_f32_e32 v92, v93, v93
	v_fmac_f32_e32 v91, v100, v100
	v_fmac_f32_e32 v92, v102, v102
	v_add_f32_e32 v91, v91, v92
	v_add_f32_e32 v103, v90, v91
	v_cvt_pk_bf16_f32 v90, v94, v95
	v_cvt_pk_bf16_f32 v91, v96, v97
	v_lshlrev_b32_e32 v96, 16, v170
	v_add_f32_e32 v86, v86, v96
	v_and_b32_e32 v96, 0xffff0000, v170
	v_add_f32_e32 v87, v87, v96
	v_lshlrev_b32_e32 v96, 16, v171
	v_add_u32_e32 v98, s10, v224
	v_add_f32_e32 v96, v88, v96
	v_and_b32_e32 v88, 0xffff0000, v171
	s_waitcnt lgkmcnt(0)
	v_ashrrev_i32_e32 v99, 31, v98
	v_add_f32_e32 v97, v89, v88
	v_lshlrev_b32_e32 v88, 16, v172
	v_lshlrev_b64 v[94:95], 12, v[98:99]
	v_add_f32_e32 v98, v82, v88
	v_and_b32_e32 v82, 0xffff0000, v172
	v_add_f32_e32 v99, v83, v82
	v_lshlrev_b32_e32 v82, 16, v173
	v_cvt_pk_bf16_f32 v92, v100, v101
	v_add_f32_e32 v100, v84, v82
	v_and_b32_e32 v82, 0xffff0000, v173
	v_add_f32_e32 v101, v85, v82
	v_mul_f32_e32 v82, v87, v87
	v_mul_f32_e32 v83, v97, v97
	v_fmac_f32_e32 v82, v86, v86
	v_fmac_f32_e32 v83, v96, v96
	v_add_f32_e32 v82, v82, v83
	v_mul_f32_e32 v83, v99, v99
	v_mul_f32_e32 v84, v101, v101
	v_fmac_f32_e32 v83, v98, v98
	v_fmac_f32_e32 v84, v100, v100
	v_add_f32_e32 v83, v83, v84
	v_add_f32_e32 v82, v82, v83
	v_add_f32_e32 v85, v103, v82
	v_cvt_pk_bf16_f32 v93, v102, v93
	v_mov_b32_e32 v102, v85
	s_nop 1
	v_permlane16_swap_b32_e32 v102, v85
	v_lshl_add_u64 v[82:83], s[12:13], 0, v[94:95]
	v_lshl_add_u64 v[88:89], v[210:211], 1, v[82:83]
	global_store_dwordx4 v[88:89], v[90:93], off
	v_cvt_pk_bf16_f32 v84, v86, v87
	s_waitcnt lgkmcnt(0)
	v_add_f32_e32 v82, v85, v102
	v_mov_b32_e32 v83, v82
	s_nop 1
	v_permlane32_swap_b32_e32 v83, v82
	v_cvt_pk_bf16_f32 v85, v96, v97
	v_cvt_pk_bf16_f32 v86, v98, v99
	v_cvt_pk_bf16_f32 v87, v100, v101
	global_store_dwordx4 v[88:89], v[84:87], off offset:256
	s_and_saveexec_b64 s[24:25], s[6:7]
	s_cbranch_execz .LBB0_187
	s_waitcnt lgkmcnt(0)
	v_add_f32_e32 v82, v82, v83
	ds_write_b32 v232, v82
; __device__ __forceinline__ unsigned cvt_pk_bf16(float lo, float hi) { unsigned r; asm volatile("v_cvt_pk_bf16_f32 %0, %1, %2" : "=v"(r) : "v"(lo), "v"(hi)); return r; }
;     __device__ __forceinline__ void operator()(const f32x4 (&acc)[2][2][4][2], const Unit& u, int wr, int wc, int fr, int fq, const float (&)[8]) const {
;     ...
;             for (int m = 0; m < 4; ++m) { const int rl = ai * HALF + wr * 64 + m * 16 + fr; const size_t off = (size_t)(u.pm * BM + rl) * ldc + col0;
;                 float ss = 0.f;
; #pragma unroll
;                 for (int bj = 0; bj < 2; ++bj) { const u32x4 b = bx[ai][m][bj];
;                     f32x4 o0, o1;
;                     o0[0] = __builtin_bit_cast(float, b.x << 16) + acc[ai][bj][m][0][0]; o0[1] = __builtin_bit_cast(float, b.x & 0xffff0000u) + acc[ai][bj][m][0][1];
;                     o0[2] = __builtin_bit_cast(float, b.y << 16) + acc[ai][bj][m][0][2]; o0[3] = __builtin_bit_cast(float, b.y & 0xffff0000u) + acc[ai][bj][m][0][3];
;                     o1[0] = __builtin_bit_cast(float, b.z << 16) + acc[ai][bj][m][1][0]; o1[1] = __builtin_bit_cast(float, b.z & 0xffff0000u) + acc[ai][bj][m][1][1];
;                     o1[2] = __builtin_bit_cast(float, b.w << 16) + acc[ai][bj][m][1][2]; o1[3] = __builtin_bit_cast(float, b.w & 0xffff0000u) + acc[ai][bj][m][1][3];
;                     if (outf) { *(f32x4*)(outf + off + bj * HALF) = o0; *(f32x4*)(outf + off + bj * HALF + 4) = o1; }
;                     else { ss += ((o0[0] * o0[0] + o0[1] * o0[1]) + (o0[2] * o0[2] + o0[3] * o0[3])) + ((o1[0] * o1[0] + o1[1] * o1[1]) + (o1[2] * o1[2] + o1[3] * o1[3]));
;                         u32x4 w; w.x = cvt_pk_bf16(o0[0], o0[1]); w.y = cvt_pk_bf16(o0[2], o0[3]); w.z = cvt_pk_bf16(o1[0], o1[1]); w.w = cvt_pk_bf16(o1[2], o1[3]); *(u32x4*)(xb + off + bj * HALF) = w; } }
;                 if (rsq_out) { ss += __shfl_xor(ss, 16); ss += __shfl_xor(ss, 32); if (fq == 0) xl[rl * 4 + wc] = ss; } }
.LBB0_187:
	s_or_b64 exec, exec, s[24:25]
	v_lshlrev_b32_e32 v84, 16, v166
	v_add_f32_e32 v78, v78, v84
	v_and_b32_e32 v84, 0xffff0000, v166
	v_add_f32_e32 v79, v79, v84
	v_lshlrev_b32_e32 v84, 16, v167
	v_add_f32_e32 v80, v80, v84
	v_and_b32_e32 v84, 0xffff0000, v167
	v_add_f32_e32 v81, v81, v84
	v_lshlrev_b32_e32 v84, 16, v168
	v_add_f32_e32 v84, v74, v84
	v_and_b32_e32 v74, 0xffff0000, v168
	v_add_f32_e32 v85, v75, v74
	v_lshlrev_b32_e32 v74, 16, v169
	v_add_f32_e32 v86, v76, v74
	v_and_b32_e32 v74, 0xffff0000, v169
	v_add_f32_e32 v77, v77, v74
	v_mul_f32_e32 v74, v79, v79
	v_mul_f32_e32 v75, v81, v81
	v_fmac_f32_e32 v74, v78, v78
	v_fmac_f32_e32 v75, v80, v80
	v_add_f32_e32 v74, v74, v75
	v_mul_f32_e32 v75, v85, v85
	v_mul_f32_e32 v76, v77, v77
	v_fmac_f32_e32 v75, v84, v84
	v_fmac_f32_e32 v76, v86, v86
	v_add_f32_e32 v75, v75, v76
	v_add_f32_e32 v87, v74, v75
	v_cvt_pk_bf16_f32 v74, v78, v79
	v_cvt_pk_bf16_f32 v75, v80, v81
	v_lshlrev_b32_e32 v80, 16, v162
	v_add_f32_e32 v70, v70, v80
	v_and_b32_e32 v80, 0xffff0000, v162
	v_add_f32_e32 v71, v71, v80
	v_lshlrev_b32_e32 v80, 16, v163
	v_add_u32_e32 v82, s10, v225
	v_add_f32_e32 v80, v72, v80
	v_and_b32_e32 v72, 0xffff0000, v163
	s_waitcnt lgkmcnt(0)
	v_ashrrev_i32_e32 v83, 31, v82
	v_add_f32_e32 v81, v73, v72
	v_lshlrev_b32_e32 v72, 16, v164
	v_lshlrev_b64 v[78:79], 12, v[82:83]
	v_add_f32_e32 v82, v66, v72
	v_and_b32_e32 v66, 0xffff0000, v164
	v_add_f32_e32 v83, v67, v66
	v_lshlrev_b32_e32 v66, 16, v165
	v_cvt_pk_bf16_f32 v76, v84, v85
	v_add_f32_e32 v84, v68, v66
	v_and_b32_e32 v66, 0xffff0000, v165
	v_add_f32_e32 v85, v69, v66
	v_mul_f32_e32 v66, v71, v71
	v_mul_f32_e32 v67, v81, v81
	v_fmac_f32_e32 v66, v70, v70
	v_fmac_f32_e32 v67, v80, v80
	v_add_f32_e32 v66, v66, v67
	v_mul_f32_e32 v67, v83, v83
	v_mul_f32_e32 v68, v85, v85
	v_fmac_f32_e32 v67, v82, v82
	v_fmac_f32_e32 v68, v84, v84
	v_add_f32_e32 v67, v67, v68
	v_add_f32_e32 v66, v66, v67
	v_add_f32_e32 v69, v87, v66
	v_cvt_pk_bf16_f32 v77, v86, v77
	v_mov_b32_e32 v86, v69
	s_nop 1
	v_permlane16_swap_b32_e32 v86, v69
	v_lshl_add_u64 v[66:67], s[12:13], 0, v[78:79]
	v_lshl_add_u64 v[72:73], v[210:211], 1, v[66:67]
	global_store_dwordx4 v[72:73], v[74:77], off
	v_cvt_pk_bf16_f32 v68, v70, v71
	s_waitcnt lgkmcnt(0)
	v_add_f32_e32 v66, v69, v86
	v_mov_b32_e32 v67, v66
	s_nop 1
	v_permlane32_swap_b32_e32 v67, v66
	v_cvt_pk_bf16_f32 v69, v80, v81
	v_cvt_pk_bf16_f32 v70, v82, v83
	v_cvt_pk_bf16_f32 v71, v84, v85
	global_store_dwordx4 v[72:73], v[68:71], off offset:256
	s_and_saveexec_b64 s[24:25], s[6:7]
	s_cbranch_execz .LBB0_189
	s_waitcnt lgkmcnt(0)
	v_add_f32_e32 v66, v66, v67
	ds_write_b32 v233, v66
.LBB0_189:
	s_or_b64 exec, exec, s[24:25]
	v_lshlrev_b32_e32 v68, 16, v158
	v_add_f32_e32 v62, v62, v68
	v_and_b32_e32 v68, 0xffff0000, v158
	v_add_f32_e32 v63, v63, v68
	v_lshlrev_b32_e32 v68, 16, v159
	v_add_f32_e32 v64, v64, v68
	v_and_b32_e32 v68, 0xffff0000, v159
	v_add_f32_e32 v65, v65, v68
	v_lshlrev_b32_e32 v68, 16, v160
	v_add_f32_e32 v68, v58, v68
	v_and_b32_e32 v58, 0xffff0000, v160
	v_add_f32_e32 v69, v59, v58
	v_lshlrev_b32_e32 v58, 16, v161
	v_add_f32_e32 v70, v60, v58
	v_and_b32_e32 v58, 0xffff0000, v161
	v_add_f32_e32 v61, v61, v58
	v_mul_f32_e32 v58, v63, v63
	v_mul_f32_e32 v59, v65, v65
	v_fmac_f32_e32 v58, v62, v62
	v_fmac_f32_e32 v59, v64, v64
	v_add_f32_e32 v58, v58, v59
	v_mul_f32_e32 v59, v69, v69
	v_mul_f32_e32 v60, v61, v61
	v_fmac_f32_e32 v59, v68, v68
	v_fmac_f32_e32 v60, v70, v70
	v_add_f32_e32 v59, v59, v60
	v_add_f32_e32 v71, v58, v59
	v_cvt_pk_bf16_f32 v58, v62, v63
	v_cvt_pk_bf16_f32 v59, v64, v65
	v_lshlrev_b32_e32 v64, 16, v154
	v_add_f32_e32 v54, v54, v64
	v_and_b32_e32 v64, 0xffff0000, v154
	v_add_f32_e32 v55, v55, v64
	v_lshlrev_b32_e32 v64, 16, v155
	v_add_u32_e32 v66, s10, v226
	v_add_f32_e32 v64, v56, v64
	v_and_b32_e32 v56, 0xffff0000, v155
	s_waitcnt lgkmcnt(0)
	v_ashrrev_i32_e32 v67, 31, v66
	v_add_f32_e32 v65, v57, v56
	v_lshlrev_b32_e32 v56, 16, v156
	v_lshlrev_b64 v[62:63], 12, v[66:67]
	v_add_f32_e32 v66, v50, v56
	v_and_b32_e32 v50, 0xffff0000, v156
	v_add_f32_e32 v67, v51, v50
	v_lshlrev_b32_e32 v50, 16, v157
	v_cvt_pk_bf16_f32 v60, v68, v69
	v_add_f32_e32 v68, v52, v50
	v_and_b32_e32 v50, 0xffff0000, v157
	v_add_f32_e32 v69, v53, v50
	v_mul_f32_e32 v50, v55, v55
	v_mul_f32_e32 v51, v65, v65
	v_fmac_f32_e32 v50, v54, v54
	v_fmac_f32_e32 v51, v64, v64
	v_add_f32_e32 v50, v50, v51
	v_mul_f32_e32 v51, v67, v67
	v_mul_f32_e32 v52, v69, v69
	v_fmac_f32_e32 v51, v66, v66
	v_fmac_f32_e32 v52, v68, v68
	v_add_f32_e32 v51, v51, v52
	v_add_f32_e32 v50, v50, v51
	v_add_f32_e32 v53, v71, v50
	v_cvt_pk_bf16_f32 v61, v70, v61
	v_mov_b32_e32 v70, v53
	s_nop 1
	v_permlane16_swap_b32_e32 v70, v53
	v_lshl_add_u64 v[50:51], s[12:13], 0, v[62:63]
	v_lshl_add_u64 v[56:57], v[210:211], 1, v[50:51]
	global_store_dwordx4 v[56:57], v[58:61], off
	v_cvt_pk_bf16_f32 v52, v54, v55
	s_waitcnt lgkmcnt(0)
	v_add_f32_e32 v50, v53, v70
	v_mov_b32_e32 v51, v50
	s_nop 1
	v_permlane32_swap_b32_e32 v51, v50
	v_cvt_pk_bf16_f32 v53, v64, v65
	v_cvt_pk_bf16_f32 v54, v66, v67
	v_cvt_pk_bf16_f32 v55, v68, v69
	global_store_dwordx4 v[56:57], v[52:55], off offset:256
	s_and_saveexec_b64 s[24:25], s[6:7]
	s_cbranch_execz .LBB0_191
	s_waitcnt lgkmcnt(0)
	v_add_f32_e32 v50, v50, v51
	ds_write_b32 v234, v50
; __device__ __forceinline__ unsigned cvt_pk_bf16(float lo, float hi) { unsigned r; asm volatile("v_cvt_pk_bf16_f32 %0, %1, %2" : "=v"(r) : "v"(lo), "v"(hi)); return r; }
;     __device__ __forceinline__ void operator()(const f32x4 (&acc)[2][2][4][2], const Unit& u, int wr, int wc, int fr, int fq, const float (&)[8]) const {
;     ...
;             for (int m = 0; m < 4; ++m) { const int rl = ai * HALF + wr * 64 + m * 16 + fr; const size_t off = (size_t)(u.pm * BM + rl) * ldc + col0;
;                 float ss = 0.f;
; #pragma unroll
;                 for (int bj = 0; bj < 2; ++bj) { const u32x4 b = bx[ai][m][bj];
;                     f32x4 o0, o1;
;                     o0[0] = __builtin_bit_cast(float, b.x << 16) + acc[ai][bj][m][0][0]; o0[1] = __builtin_bit_cast(float, b.x & 0xffff0000u) + acc[ai][bj][m][0][1];
;                     o0[2] = __builtin_bit_cast(float, b.y << 16) + acc[ai][bj][m][0][2]; o0[3] = __builtin_bit_cast(float, b.y & 0xffff0000u) + acc[ai][bj][m][0][3];
;                     o1[0] = __builtin_bit_cast(float, b.z << 16) + acc[ai][bj][m][1][0]; o1[1] = __builtin_bit_cast(float, b.z & 0xffff0000u) + acc[ai][bj][m][1][1];
;                     o1[2] = __builtin_bit_cast(float, b.w << 16) + acc[ai][bj][m][1][2]; o1[3] = __builtin_bit_cast(float, b.w & 0xffff0000u) + acc[ai][bj][m][1][3];
;                     if (outf) { *(f32x4*)(outf + off + bj * HALF) = o0; *(f32x4*)(outf + off + bj * HALF + 4) = o1; }
;                     else { ss += ((o0[0] * o0[0] + o0[1] * o0[1]) + (o0[2] * o0[2] + o0[3] * o0[3])) + ((o1[0] * o1[0] + o1[1] * o1[1]) + (o1[2] * o1[2] + o1[3] * o1[3]));
;                         u32x4 w; w.x = cvt_pk_bf16(o0[0], o0[1]); w.y = cvt_pk_bf16(o0[2], o0[3]); w.z = cvt_pk_bf16(o1[0], o1[1]); w.w = cvt_pk_bf16(o1[2], o1[3]); *(u32x4*)(xb + off + bj * HALF) = w; } }
;                 if (rsq_out) { ss += __shfl_xor(ss, 16); ss += __shfl_xor(ss, 32); if (fq == 0) xl[rl * 4 + wc] = ss; } }
.LBB0_191:
	s_or_b64 exec, exec, s[24:25]
	v_lshlrev_b32_e32 v52, 16, v150
	v_add_f32_e32 v46, v46, v52
	v_and_b32_e32 v52, 0xffff0000, v150
	v_add_f32_e32 v47, v47, v52
	v_lshlrev_b32_e32 v52, 16, v151
	v_add_f32_e32 v48, v48, v52
	v_and_b32_e32 v52, 0xffff0000, v151
	v_add_f32_e32 v49, v49, v52
	v_lshlrev_b32_e32 v52, 16, v152
	v_add_f32_e32 v52, v42, v52
	v_and_b32_e32 v42, 0xffff0000, v152
	v_add_f32_e32 v53, v43, v42
	v_lshlrev_b32_e32 v42, 16, v153
	v_add_f32_e32 v54, v44, v42
	v_and_b32_e32 v42, 0xffff0000, v153
	v_add_f32_e32 v45, v45, v42
	v_mul_f32_e32 v42, v47, v47
	v_mul_f32_e32 v43, v49, v49
	v_fmac_f32_e32 v42, v46, v46
	v_fmac_f32_e32 v43, v48, v48
	v_add_f32_e32 v42, v42, v43
	v_mul_f32_e32 v43, v53, v53
	v_mul_f32_e32 v44, v45, v45
	v_fmac_f32_e32 v43, v52, v52
	v_fmac_f32_e32 v44, v54, v54
	v_add_f32_e32 v43, v43, v44
	v_add_f32_e32 v55, v42, v43
	v_cvt_pk_bf16_f32 v42, v46, v47
	v_cvt_pk_bf16_f32 v43, v48, v49
	v_lshlrev_b32_e32 v48, 16, v138
	v_add_f32_e32 v38, v38, v48
	v_and_b32_e32 v48, 0xffff0000, v138
	v_add_f32_e32 v39, v39, v48
	v_lshlrev_b32_e32 v48, 16, v139
	v_add_u32_e32 v50, s10, v227
	v_add_f32_e32 v48, v40, v48
	v_and_b32_e32 v40, 0xffff0000, v139
	s_waitcnt lgkmcnt(0)
	v_ashrrev_i32_e32 v51, 31, v50
	v_add_f32_e32 v49, v41, v40
	v_lshlrev_b32_e32 v40, 16, v140
	v_lshlrev_b64 v[46:47], 12, v[50:51]
	v_add_f32_e32 v50, v34, v40
	v_and_b32_e32 v34, 0xffff0000, v140
	v_add_f32_e32 v51, v35, v34
	v_lshlrev_b32_e32 v34, 16, v141
	v_cvt_pk_bf16_f32 v44, v52, v53
	v_add_f32_e32 v52, v36, v34
	v_and_b32_e32 v34, 0xffff0000, v141
	v_add_f32_e32 v53, v37, v34
	v_mul_f32_e32 v34, v39, v39
	v_mul_f32_e32 v35, v49, v49
	v_fmac_f32_e32 v34, v38, v38
	v_fmac_f32_e32 v35, v48, v48
	v_add_f32_e32 v34, v34, v35
	v_mul_f32_e32 v35, v51, v51
	v_mul_f32_e32 v36, v53, v53
	v_fmac_f32_e32 v35, v50, v50
	v_fmac_f32_e32 v36, v52, v52
	v_add_f32_e32 v35, v35, v36
	v_add_f32_e32 v34, v34, v35
	v_add_f32_e32 v37, v55, v34
	v_cvt_pk_bf16_f32 v45, v54, v45
	v_mov_b32_e32 v54, v37
	s_nop 1
	v_permlane16_swap_b32_e32 v54, v37
	v_lshl_add_u64 v[34:35], s[12:13], 0, v[46:47]
	v_lshl_add_u64 v[40:41], v[210:211], 1, v[34:35]
	global_store_dwordx4 v[40:41], v[42:45], off
	v_cvt_pk_bf16_f32 v36, v38, v39
	s_waitcnt lgkmcnt(0)
	v_add_f32_e32 v34, v37, v54
	v_mov_b32_e32 v35, v34
	s_nop 1
	v_permlane32_swap_b32_e32 v35, v34
	v_cvt_pk_bf16_f32 v37, v48, v49
	v_cvt_pk_bf16_f32 v38, v50, v51
	v_cvt_pk_bf16_f32 v39, v52, v53
	global_store_dwordx4 v[40:41], v[36:39], off offset:256
	s_and_saveexec_b64 s[24:25], s[6:7]
	s_cbranch_execz .LBB0_193
	s_waitcnt lgkmcnt(0)
	v_add_f32_e32 v34, v34, v35
	ds_write_b32 v235, v34
; __device__ __forceinline__ unsigned cvt_pk_bf16(float lo, float hi) { unsigned r; asm volatile("v_cvt_pk_bf16_f32 %0, %1, %2" : "=v"(r) : "v"(lo), "v"(hi)); return r; }
;     __device__ __forceinline__ void operator()(const f32x4 (&acc)[2][2][4][2], const Unit& u, int wr, int wc, int fr, int fq, const float (&)[8]) const {
;     ...
;             for (int m = 0; m < 4; ++m) { const int rl = ai * HALF + wr * 64 + m * 16 + fr; const size_t off = (size_t)(u.pm * BM + rl) * ldc + col0;
;                 float ss = 0.f;
; #pragma unroll
;                 for (int bj = 0; bj < 2; ++bj) { const u32x4 b = bx[ai][m][bj];
;                     f32x4 o0, o1;
;                     o0[0] = __builtin_bit_cast(float, b.x << 16) + acc[ai][bj][m][0][0]; o0[1] = __builtin_bit_cast(float, b.x & 0xffff0000u) + acc[ai][bj][m][0][1];
;                     o0[2] = __builtin_bit_cast(float, b.y << 16) + acc[ai][bj][m][0][2]; o0[3] = __builtin_bit_cast(float, b.y & 0xffff0000u) + acc[ai][bj][m][0][3];
;                     o1[0] = __builtin_bit_cast(float, b.z << 16) + acc[ai][bj][m][1][0]; o1[1] = __builtin_bit_cast(float, b.z & 0xffff0000u) + acc[ai][bj][m][1][1];
;                     o1[2] = __builtin_bit_cast(float, b.w << 16) + acc[ai][bj][m][1][2]; o1[3] = __builtin_bit_cast(float, b.w & 0xffff0000u) + acc[ai][bj][m][1][3];
;                     if (outf) { *(f32x4*)(outf + off + bj * HALF) = o0; *(f32x4*)(outf + off + bj * HALF + 4) = o1; }
;                     else { ss += ((o0[0] * o0[0] + o0[1] * o0[1]) + (o0[2] * o0[2] + o0[3] * o0[3])) + ((o1[0] * o1[0] + o1[1] * o1[1]) + (o1[2] * o1[2] + o1[3] * o1[3]));
;                         u32x4 w; w.x = cvt_pk_bf16(o0[0], o0[1]); w.y = cvt_pk_bf16(o0[2], o0[3]); w.z = cvt_pk_bf16(o1[0], o1[1]); w.w = cvt_pk_bf16(o1[2], o1[3]); *(u32x4*)(xb + off + bj * HALF) = w; } }
;                 if (rsq_out) { ss += __shfl_xor(ss, 16); ss += __shfl_xor(ss, 32); if (fq == 0) xl[rl * 4 + wc] = ss; } }
.LBB0_193:
	s_or_b64 exec, exec, s[24:25]
	v_lshlrev_b32_e32 v36, 16, v130
	v_add_f32_e32 v30, v30, v36
	v_and_b32_e32 v36, 0xffff0000, v130
	v_add_f32_e32 v31, v31, v36
	v_lshlrev_b32_e32 v36, 16, v131
	v_add_f32_e32 v32, v32, v36
	v_and_b32_e32 v36, 0xffff0000, v131
	v_add_f32_e32 v33, v33, v36
	v_lshlrev_b32_e32 v36, 16, v132
	v_add_f32_e32 v36, v26, v36
	v_and_b32_e32 v26, 0xffff0000, v132
	v_add_f32_e32 v37, v27, v26
	v_lshlrev_b32_e32 v26, 16, v133
	v_add_f32_e32 v38, v28, v26
	v_and_b32_e32 v26, 0xffff0000, v133
	v_add_f32_e32 v29, v29, v26
	v_mul_f32_e32 v26, v31, v31
	v_mul_f32_e32 v27, v33, v33
	v_fmac_f32_e32 v26, v30, v30
	v_fmac_f32_e32 v27, v32, v32
	v_add_f32_e32 v26, v26, v27
	v_mul_f32_e32 v27, v37, v37
	v_mul_f32_e32 v28, v29, v29
	v_fmac_f32_e32 v27, v36, v36
	v_fmac_f32_e32 v28, v38, v38
	v_add_f32_e32 v27, v27, v28
	v_add_f32_e32 v39, v26, v27
	v_cvt_pk_bf16_f32 v26, v30, v31
	v_cvt_pk_bf16_f32 v27, v32, v33
	v_lshlrev_b32_e32 v32, 16, v122
	v_add_f32_e32 v22, v22, v32
	v_and_b32_e32 v32, 0xffff0000, v122
	v_add_f32_e32 v23, v23, v32
	v_lshlrev_b32_e32 v32, 16, v123
	v_add_u32_e32 v34, s10, v228
	v_add_f32_e32 v32, v24, v32
	v_and_b32_e32 v24, 0xffff0000, v123
	s_waitcnt lgkmcnt(0)
	v_ashrrev_i32_e32 v35, 31, v34
	v_add_f32_e32 v33, v25, v24
	v_lshlrev_b32_e32 v24, 16, v124
	v_lshlrev_b64 v[30:31], 12, v[34:35]
	v_add_f32_e32 v34, v18, v24
	v_and_b32_e32 v18, 0xffff0000, v124
	v_add_f32_e32 v35, v19, v18
	v_lshlrev_b32_e32 v18, 16, v125
	v_cvt_pk_bf16_f32 v28, v36, v37
	v_add_f32_e32 v36, v20, v18
	v_and_b32_e32 v18, 0xffff0000, v125
	v_add_f32_e32 v37, v21, v18
	v_mul_f32_e32 v18, v23, v23
	v_mul_f32_e32 v19, v33, v33
	v_fmac_f32_e32 v18, v22, v22
	v_fmac_f32_e32 v19, v32, v32
	v_add_f32_e32 v18, v18, v19
	v_mul_f32_e32 v19, v35, v35
	v_mul_f32_e32 v20, v37, v37
	v_fmac_f32_e32 v19, v34, v34
	v_fmac_f32_e32 v20, v36, v36
	v_add_f32_e32 v19, v19, v20
	v_add_f32_e32 v18, v18, v19
	v_add_f32_e32 v21, v39, v18
	v_cvt_pk_bf16_f32 v29, v38, v29
	v_mov_b32_e32 v38, v21
	s_nop 1
	v_permlane16_swap_b32_e32 v38, v21
	v_lshl_add_u64 v[18:19], s[12:13], 0, v[30:31]
	v_lshl_add_u64 v[24:25], v[210:211], 1, v[18:19]
	global_store_dwordx4 v[24:25], v[26:29], off
	v_cvt_pk_bf16_f32 v20, v22, v23
	s_waitcnt lgkmcnt(0)
	v_add_f32_e32 v18, v21, v38
	v_mov_b32_e32 v19, v18
	s_nop 1
	v_permlane32_swap_b32_e32 v19, v18
	v_cvt_pk_bf16_f32 v21, v32, v33
	v_cvt_pk_bf16_f32 v22, v34, v35
	v_cvt_pk_bf16_f32 v23, v36, v37
	global_store_dwordx4 v[24:25], v[20:23], off offset:256
	s_and_saveexec_b64 s[24:25], s[6:7]
	s_cbranch_execz .LBB0_195
	s_waitcnt lgkmcnt(0)
	v_add_f32_e32 v18, v18, v19
	ds_write_b32 v236, v18
.LBB0_195:
	s_or_b64 exec, exec, s[24:25]
	v_lshlrev_b32_e32 v20, 16, v142
	v_add_f32_e32 v14, v14, v20
	v_and_b32_e32 v20, 0xffff0000, v142
	v_add_f32_e32 v15, v15, v20
	v_lshlrev_b32_e32 v20, 16, v143
	v_add_f32_e32 v16, v16, v20
	v_and_b32_e32 v20, 0xffff0000, v143
	v_add_f32_e32 v17, v17, v20
	v_lshlrev_b32_e32 v20, 16, v144
	v_add_f32_e32 v20, v10, v20
	v_and_b32_e32 v10, 0xffff0000, v144
	v_add_f32_e32 v21, v11, v10
	v_lshlrev_b32_e32 v10, 16, v145
	v_add_f32_e32 v22, v12, v10
	v_and_b32_e32 v10, 0xffff0000, v145
	v_add_f32_e32 v13, v13, v10
	v_mul_f32_e32 v10, v15, v15
	v_mul_f32_e32 v11, v17, v17
	v_fmac_f32_e32 v10, v14, v14
	v_fmac_f32_e32 v11, v16, v16
	v_add_f32_e32 v10, v10, v11
	v_mul_f32_e32 v11, v21, v21
	v_mul_f32_e32 v12, v13, v13
	v_fmac_f32_e32 v11, v20, v20
	v_fmac_f32_e32 v12, v22, v22
	v_add_f32_e32 v11, v11, v12
	v_add_f32_e32 v23, v10, v11
	v_cvt_pk_bf16_f32 v10, v14, v15
	v_cvt_pk_bf16_f32 v11, v16, v17
	v_lshlrev_b32_e32 v16, 16, v126
	v_add_f32_e32 v6, v6, v16
	v_and_b32_e32 v16, 0xffff0000, v126
	v_add_f32_e32 v7, v7, v16
	v_lshlrev_b32_e32 v16, 16, v127
	v_add_u32_e32 v18, s10, v229
	v_add_f32_e32 v16, v8, v16
	v_and_b32_e32 v8, 0xffff0000, v127
	s_waitcnt lgkmcnt(0)
	v_ashrrev_i32_e32 v19, 31, v18
	v_add_f32_e32 v17, v9, v8
	v_lshlrev_b32_e32 v8, 16, v128
	v_lshlrev_b64 v[14:15], 12, v[18:19]
	v_add_f32_e32 v18, v2, v8
	v_and_b32_e32 v2, 0xffff0000, v128
	v_add_f32_e32 v19, v3, v2
	v_lshlrev_b32_e32 v2, 16, v129
	v_cvt_pk_bf16_f32 v12, v20, v21
	v_add_f32_e32 v20, v4, v2
	v_and_b32_e32 v2, 0xffff0000, v129
	v_add_f32_e32 v21, v5, v2
	v_mul_f32_e32 v2, v7, v7
	v_mul_f32_e32 v3, v17, v17
	v_fmac_f32_e32 v2, v6, v6
	v_fmac_f32_e32 v3, v16, v16
	v_add_f32_e32 v2, v2, v3
	v_mul_f32_e32 v3, v19, v19
	v_mul_f32_e32 v4, v21, v21
	v_fmac_f32_e32 v3, v18, v18
	v_fmac_f32_e32 v4, v20, v20
	v_add_f32_e32 v3, v3, v4
	v_add_f32_e32 v2, v2, v3
	v_add_f32_e32 v5, v23, v2
	v_cvt_pk_bf16_f32 v13, v22, v13
	v_mov_b32_e32 v22, v5
	s_nop 1
	v_permlane16_swap_b32_e32 v22, v5
	v_lshl_add_u64 v[2:3], s[12:13], 0, v[14:15]
	v_lshl_add_u64 v[8:9], v[210:211], 1, v[2:3]
	global_store_dwordx4 v[8:9], v[10:13], off
	v_cvt_pk_bf16_f32 v4, v6, v7
	s_waitcnt lgkmcnt(0)
	v_add_f32_e32 v2, v5, v22
	v_mov_b32_e32 v3, v2
	s_nop 1
	v_permlane32_swap_b32_e32 v3, v2
	v_cvt_pk_bf16_f32 v5, v16, v17
	v_cvt_pk_bf16_f32 v6, v18, v19
	v_cvt_pk_bf16_f32 v7, v20, v21
	global_store_dwordx4 v[8:9], v[4:7], off offset:256
	s_and_saveexec_b64 s[24:25], s[6:7]
	s_cbranch_execz .LBB0_197
	s_waitcnt lgkmcnt(0)
	v_add_f32_e32 v2, v2, v3
	ds_write_b32 v237, v2

; __device__ __forceinline__ void merge_rows(bf16_t* Z, const float* LSE, const float* ga, const float* gb, int gw, int ngw, int lane) {
;     ...
;     for (int m0 = gw; m0 < M; m0 += 2 * ngw) {
;         u32x4 q0[2][2], q1[2][2], q2[2][2], aa[2][2]; float l0[2], l1[2], l2[2]; bool ok[2];
; #pragma unroll
;         for (int r = 0; r < 2; ++r) { const int m = m0 + r * ngw; ok[r] = m < M; const int mm = ok[r] ? m : m0; const bf16_t* zr = Z + (size_t)mm * INW;
;             l0[r] = LSE[((size_t)0 * M + mm) * 8 + head]; l1[r] = LSE[((size_t)1 * M + mm) * 8 + head]; l2[r] = LSE[((size_t)2 * M + mm) * 8 + head];
; #pragma unroll
;             for (int h2 = 0; h2 < 2; ++h2) { q0[r][h2] = *(const u32x4*)(zr + C_Q + ch0 + 8 * h2); q1[r][h2] = *(const u32x4*)(zr + C_Q + 1024 + ch0 + 8 * h2); q2[r][h2] = *(const u32x4*)(zr + C_Q + 2048 + ch0 + 8 * h2); aa[r][h2] = *(const u32x4*)(zr + ch0 + 8 * h2); } }
; #pragma unroll
;         for (int r = 0; r < 2; ++r) {
;             const float mx = fmaxf(l0[r], fmaxf(l1[r], l2[r]));
;             float e0 = __builtin_amdgcn_exp2f((l0[r] - mx) * 1.4426950408889634f), e1 = __builtin_amdgcn_exp2f((l1[r] - mx) * 1.4426950408889634f), e2 = __builtin_amdgcn_exp2f((l2[r] - mx) * 1.4426950408889634f);
;             const float inv = __builtin_amdgcn_rcpf(e0 + e1 + e2); e0 *= inv; e1 *= inv; e2 *= inv;
;             float ob[16], oa[16];
; #pragma unroll
;             for (int h2 = 0; h2 < 2; ++h2)
; #pragma unroll
;                 for (int e = 0; e < 4; ++e) {
;                     ob[8 * h2 + 2 * e] = e0 * bf_lo(q0[r][h2][e]) + e1 * bf_lo(q1[r][h2][e]) + e2 * bf_lo(q2[r][h2][e]); ob[8 * h2 + 2 * e + 1] = e0 * bf_hi(q0[r][h2][e]) + e1 * bf_hi(q1[r][h2][e]) + e2 * bf_hi(q2[r][h2][e]);
.LBB0_208:
	s_ashr_i32 s11, s10, 31
	s_mul_i32 s7, s10, 0x3800
	s_mul_hi_i32 s6, s10, 0x3800
	s_add_u32 s8, s0, s7
	s_addc_u32 s9, s1, s6
	s_lshl_b64 s[6:7], s[10:11], 5
	s_add_u32 s6, s13, s6
	s_addc_u32 s7, s14, s7
	v_lshl_add_u64 v[34:35], s[6:7], 0, v[196:197]
	v_mov_b32_e32 v75, v197
	v_add_co_u32_e32 v36, vcc, s86, v34
	v_lshl_add_u64 v[46:47], s[8:9], 0, v[74:75]
	global_load_dword v90, v196, s[6:7]
	global_load_dwordx4 v[42:45], v74, s[8:9]
	v_addc_co_u32_e32 v37, vcc, 0, v35, vcc
	s_mov_b32 s15, 0x100000
	v_add_co_u32_e64 v38, s[6:7], s72, v46
	v_add_co_u32_e32 v34, vcc, s15, v34
	s_nop 0
	v_addc_co_u32_e64 v39, s[6:7], 0, v47, s[6:7]
	global_load_dwordx4 v[54:57], v[38:39], off offset:2048
	v_addc_co_u32_e32 v35, vcc, 0, v35, vcc
	global_load_dword v91, v[36:37], off
	global_load_dword v92, v[34:35], off
	v_add_co_u32_e32 v34, vcc, s85, v46
	s_mov_b64 s[18:19], 0x1000
	s_nop 0
	v_addc_co_u32_e32 v35, vcc, 0, v47, vcc
	s_waitcnt lgkmcnt(0)
	global_load_dwordx4 v[58:61], v[34:35], off offset:-4096
	global_load_dwordx4 v[62:65], v[34:35], off
	global_load_dwordx4 v[38:41], v74, s[8:9] offset:16
	s_mov_b64 s[20:21], 0x1800
	s_mov_b64 s[22:23], 0x2000
	v_lshl_add_u64 v[34:35], v[46:47], 0, s[18:19]
	v_lshl_add_u64 v[36:37], v[46:47], 0, s[20:21]
	v_lshl_add_u64 v[46:47], v[46:47], 0, s[22:23]
	global_load_dwordx4 v[50:53], v[36:37], off offset:16
	s_nop 0
	global_load_dwordx4 v[46:49], v[46:47], off offset:16
	s_add_i32 s11, s10, s12
	global_load_dwordx4 v[66:69], v[34:35], off offset:16
	s_cmpk_lt_i32 s11, 0x4000
	s_cselect_b32 s16, s11, s10
	s_ashr_i32 s17, s16, 31
	s_mul_i32 s6, s16, 0x3800
	s_mul_hi_i32 s7, s16, 0x3800
	s_add_u32 s6, s0, s6
	s_addc_u32 s7, s1, s7
	s_lshl_b64 s[16:17], s[16:17], 5
	s_add_u32 s16, s13, s16
	v_lshl_add_u64 v[70:71], s[6:7], 0, v[74:75]
	s_addc_u32 s17, s14, s17
	v_add_co_u32_e32 v76, vcc, s85, v70
	v_lshl_add_u64 v[84:85], s[16:17], 0, v[196:197]
	s_nop 0
	v_addc_co_u32_e32 v77, vcc, 0, v71, vcc
	v_add_co_u32_e32 v86, vcc, s86, v84
	global_load_dword v75, v196, s[16:17]
	global_load_dwordx4 v[34:37], v[76:77], off offset:-4096
	v_addc_co_u32_e32 v87, vcc, 0, v85, vcc
	v_add_co_u32_e32 v88, vcc, s15, v84
	s_cmpk_gt_i32 s11, 0x3fff
	s_nop 0
	v_addc_co_u32_e32 v89, vcc, 0, v85, vcc
	global_load_dword v84, v[86:87], off
	global_load_dword v83, v[88:89], off
	s_waitcnt vmcnt(0)
	v_lshlrev_b32_e32 v89, 16, v42
	v_and_b32_e32 v93, 0xffff0000, v42
	v_lshlrev_b32_e32 v94, 16, v43
	v_and_b32_e32 v95, 0xffff0000, v43
	v_lshlrev_b32_e32 v96, 16, v44
	v_and_b32_e32 v97, 0xffff0000, v44
	v_and_b32_e32 v104, 0xffff0000, v45
	v_lshlrev_b32_e32 v85, 16, v54
	v_and_b32_e32 v88, 0xffff0000, v54
	v_lshlrev_b32_e32 v98, 16, v55
	v_max3_f32 v42, v90, v91, v92
	v_sub_f32_e32 v43, v90, v42
	v_sub_f32_e32 v44, v91, v42
	v_sub_f32_e32 v42, v92, v42
	v_mul_f32_e32 v43, 0x3fb8aa3b, v43
	v_mul_f32_e32 v44, 0x3fb8aa3b, v44
	v_mul_f32_e32 v42, 0x3fb8aa3b, v42
	v_exp_f32_e32 v43, v43
	v_exp_f32_e32 v86, v44
	v_exp_f32_e32 v42, v42
	v_and_b32_e32 v99, 0xffff0000, v55
	v_lshlrev_b32_e32 v55, 16, v58
	v_add_f32_e32 v44, v43, v86
	v_add_f32_e32 v44, v42, v44
	v_rcp_f32_e32 v44, v44
	v_lshlrev_b32_e32 v54, 16, v62
	v_and_b32_e32 v87, 0xffff0000, v58
	v_lshlrev_b32_e32 v100, 16, v56
	v_pk_mul_f32 v[42:43], v[42:43], v[44:45] op_sel_hi:[1,0]
	v_mul_f32_e32 v58, v86, v44
	v_pk_mul_f32 v[54:55], v[42:43], v[54:55]
	v_and_b32_e32 v86, 0xffff0000, v62
	v_fma_f32 v44, v58, v85, v55
	v_add_f32_e32 v91, v54, v44
	v_pk_mul_f32 v[54:55], v[42:43], v[86:87]
	v_and_b32_e32 v56, 0xffff0000, v56
	v_fma_f32 v44, v58, v88, v55
	v_add_f32_e32 v92, v54, v44
	v_lshlrev_b32_e32 v55, 16, v59
	v_lshlrev_b32_e32 v54, 16, v63
	v_pk_mul_f32 v[54:55], v[42:43], v[54:55]
	v_lshlrev_b32_e32 v90, 16, v57
	v_fma_f32 v44, v58, v98, v55
	v_add_f32_e32 v98, v54, v44
	v_and_b32_e32 v55, 0xffff0000, v59
	v_and_b32_e32 v54, 0xffff0000, v63
	v_pk_mul_f32 v[54:55], v[42:43], v[54:55]
	v_lshlrev_b32_e32 v107, 16, v38
	v_fma_f32 v44, v58, v99, v55
	v_add_f32_e32 v99, v54, v44
	v_lshlrev_b32_e32 v55, 16, v60
	v_lshlrev_b32_e32 v54, 16, v64
	v_pk_mul_f32 v[54:55], v[42:43], v[54:55]
	v_and_b32_e32 v108, 0xffff0000, v38
	v_fma_f32 v44, v58, v100, v55
	v_add_f32_e32 v100, v54, v44
	v_and_b32_e32 v55, 0xffff0000, v60
	v_and_b32_e32 v54, 0xffff0000, v64
	v_pk_mul_f32 v[54:55], v[42:43], v[54:55]
	v_lshlrev_b32_e32 v38, 16, v51
	v_fma_f32 v44, v58, v56, v55
	v_add_f32_e32 v101, v54, v44
	v_lshlrev_b32_e32 v55, 16, v61
	v_lshlrev_b32_e32 v54, 16, v65
	v_pk_mul_f32 v[54:55], v[42:43], v[54:55]
	v_lshlrev_b32_e32 v111, 16, v39
	v_fma_f32 v44, v58, v90, v55
	v_add_f32_e32 v102, v54, v44
	v_and_b32_e32 v55, 0xffff0000, v61
	v_and_b32_e32 v54, 0xffff0000, v65
	v_and_b32_e32 v44, 0xffff0000, v57
	v_pk_mul_f32 v[54:55], v[42:43], v[54:55]
	v_lshlrev_b32_e32 v90, 16, v45
	v_fma_f32 v44, v58, v44, v55
	v_add_f32_e32 v103, v54, v44
	v_lshlrev_b32_e32 v45, 16, v66
	v_lshlrev_b32_e32 v44, 16, v46
	v_lshlrev_b32_e32 v54, 16, v50
	v_pk_mul_f32 v[44:45], v[42:43], v[44:45]
	v_and_b32_e32 v50, 0xffff0000, v50
	v_fma_f32 v45, v58, v54, v45
	v_add_f32_e32 v105, v45, v44
	v_and_b32_e32 v45, 0xffff0000, v66
	v_and_b32_e32 v44, 0xffff0000, v46
	v_pk_mul_f32 v[44:45], v[42:43], v[44:45]
	v_and_b32_e32 v112, 0xffff0000, v39
	v_fma_f32 v45, v58, v50, v45
	v_add_f32_e32 v106, v45, v44
	v_lshlrev_b32_e32 v45, 16, v67
	v_lshlrev_b32_e32 v44, 16, v47
	v_pk_mul_f32 v[44:45], v[42:43], v[44:45]
	v_lshlrev_b32_e32 v39, 16, v68
	v_fma_f32 v38, v58, v38, v45
	v_add_f32_e32 v109, v38, v44
	v_and_b32_e32 v45, 0xffff0000, v67
	v_and_b32_e32 v44, 0xffff0000, v47
	v_and_b32_e32 v38, 0xffff0000, v51
; __device__ __forceinline__ void merge_rows(bf16_t* Z, const float* LSE, const float* ga, const float* gb, int gw, int ngw, int lane) {
;     ...
;         for (int r = 0; r < 2; ++r) {
;             const float mx = fmaxf(l0[r], fmaxf(l1[r], l2[r]));
;             float e0 = __builtin_amdgcn_exp2f((l0[r] - mx) * 1.4426950408889634f), e1 = __builtin_amdgcn_exp2f((l1[r] - mx) * 1.4426950408889634f), e2 = __builtin_amdgcn_exp2f((l2[r] - mx) * 1.4426950408889634f);
;             const float inv = __builtin_amdgcn_rcpf(e0 + e1 + e2); e0 *= inv; e1 *= inv; e2 *= inv;
;             float ob[16], oa[16];
; #pragma unroll
;             for (int h2 = 0; h2 < 2; ++h2)
; #pragma unroll
;                 for (int e = 0; e < 4; ++e) {
;                     ob[8 * h2 + 2 * e] = e0 * bf_lo(q0[r][h2][e]) + e1 * bf_lo(q1[r][h2][e]) + e2 * bf_lo(q2[r][h2][e]); ob[8 * h2 + 2 * e + 1] = e0 * bf_hi(q0[r][h2][e]) + e1 * bf_hi(q1[r][h2][e]) + e2 * bf_hi(q2[r][h2][e]);
;                     oa[8 * h2 + 2 * e] = bf_lo(aa[r][h2][e]); oa[8 * h2 + 2 * e + 1] = bf_hi(aa[r][h2][e]); }
;             float sb = 0.f, sa = 0.f;
; #pragma unroll
;             for (int c = 0; c < 16; ++c) { sb += ob[c] * ob[c]; sa += oa[c] * oa[c]; }
;             sb = wave_sum(sb); sa = wave_sum(sa);
;             const float rb = __builtin_amdgcn_rsqf(sb * (1.f / 1024.f) + EPS), ra = __builtin_amdgcn_rsqf(sa * (1.f / 1024.f) + EPS);
;             bf16_t* mr = Z + (size_t)(m0 + r * ngw) * INW;
;             if (ok[r]) {
; #pragma unroll
;                 for (int h2 = 0; h2 < 2; ++h2) {
;                     const f32x4 ga0 = gav[h2][0], ga1 = gav[h2][1], gb0 = gbv[h2][0], gb1 = gbv[h2][1];
;                     u32x4 wa, wb; const float* A = oa + 8 * h2; const float* B = ob + 8 * h2;
;                     wa.x = pk2(A[0] * ra * ga0[0], A[1] * ra * ga0[1]); wa.y = pk2(A[2] * ra * ga0[2], A[3] * ra * ga0[3]); wa.z = pk2(A[4] * ra * ga1[0], A[5] * ra * ga1[1]); wa.w = pk2(A[6] * ra * ga1[2], A[7] * ra * ga1[3]);
;                     wb.x = pk2(B[0] * rb * gb0[0], B[1] * rb * gb0[1]); wb.y = pk2(B[2] * rb * gb0[2], B[3] * rb * gb0[3]); wb.z = pk2(B[4] * rb * gb1[0], B[5] * rb * gb1[1]); wb.w = pk2(B[6] * rb * gb1[2], B[7] * rb * gb1[3]);
;                     *(u32x4*)(mr + ch0 + 8 * h2) = wa; *(u32x4*)(mr + 1024 + ch0 + 8 * h2) = wb;
	v_pk_mul_f32 v[44:45], v[42:43], v[44:45]
	v_lshlrev_b32_e32 v113, 16, v40
	v_fma_f32 v38, v58, v38, v45
	v_add_f32_e32 v110, v38, v44
	v_lshlrev_b32_e32 v38, 16, v48
	v_lshlrev_b32_e32 v44, 16, v52
	v_pk_mul_f32 v[38:39], v[42:43], v[38:39]
	v_and_b32_e32 v114, 0xffff0000, v40
	v_fma_f32 v39, v58, v44, v39
	v_add_f32_e32 v88, v39, v38
	v_and_b32_e32 v39, 0xffff0000, v68
	v_and_b32_e32 v38, 0xffff0000, v48
	v_and_b32_e32 v44, 0xffff0000, v52
	v_pk_mul_f32 v[38:39], v[42:43], v[38:39]
	v_lshlrev_b32_e32 v40, 16, v53
	v_fma_f32 v39, v58, v44, v39
	v_add_f32_e32 v87, v39, v38
	v_lshlrev_b32_e32 v39, 16, v69
	v_lshlrev_b32_e32 v38, 16, v49
	v_pk_mul_f32 v[38:39], v[42:43], v[38:39]
	v_lshlrev_b32_e32 v115, 16, v41
	v_fma_f32 v39, v58, v40, v39
	v_add_f32_e32 v86, v39, v38
	v_and_b32_e32 v39, 0xffff0000, v69
	v_and_b32_e32 v38, 0xffff0000, v49
	v_and_b32_e32 v40, 0xffff0000, v53
	v_pk_mul_f32 v[38:39], v[42:43], v[38:39]
	v_and_b32_e32 v116, 0xffff0000, v41
	v_fma_f32 v39, v58, v40, v39
	v_mul_f32_e32 v40, v92, v92
	v_mul_f32_e32 v41, v93, v93
	v_fmac_f32_e32 v40, v91, v91
	v_fmac_f32_e32 v41, v89, v89
	v_fmac_f32_e32 v40, v98, v98
	v_fmac_f32_e32 v41, v94, v94
	v_fmac_f32_e32 v40, v99, v99
	v_fmac_f32_e32 v41, v95, v95
	v_fmac_f32_e32 v40, v100, v100
	v_fmac_f32_e32 v41, v96, v96
	v_fmac_f32_e32 v40, v101, v101
	v_fmac_f32_e32 v41, v97, v97
	v_fmac_f32_e32 v40, v102, v102
	v_fmac_f32_e32 v41, v90, v90
	v_fmac_f32_e32 v40, v103, v103
	v_fmac_f32_e32 v41, v104, v104
	v_fmac_f32_e32 v40, v105, v105
	v_fmac_f32_e32 v41, v107, v107
	v_fmac_f32_e32 v40, v106, v106
	v_fmac_f32_e32 v41, v108, v108
	v_fmac_f32_e32 v40, v109, v109
	v_fmac_f32_e32 v41, v111, v111
	v_fmac_f32_e32 v40, v110, v110
	v_fmac_f32_e32 v41, v112, v112
	v_fmac_f32_e32 v40, v88, v88
	v_fmac_f32_e32 v41, v113, v113
	v_fmac_f32_e32 v40, v87, v87
	v_fmac_f32_e32 v41, v114, v114
	v_add_f32_e32 v85, v39, v38
	v_fmac_f32_e32 v40, v86, v86
	v_fmac_f32_e32 v41, v115, v115
	v_fmac_f32_e32 v40, v85, v85
	v_fmac_f32_e32 v41, v116, v116
	s_nop 1
	v_mov_b32_dpp v42, v40 quad_perm:[1,0,3,2] row_mask:0xf bank_mask:0xf
	s_nop 1
	v_mov_b32_dpp v43, v41 quad_perm:[1,0,3,2] row_mask:0xf bank_mask:0xf
	v_add_co_u32_e32 v52, vcc, s72, v70
	v_lshl_add_u64 v[38:39], v[70:71], 0, s[18:19]
	s_waitcnt lgkmcnt(1)
	v_add_f32_e32 v42, v40, v42
	s_waitcnt lgkmcnt(0)
	v_add_f32_e32 v43, v41, v43
	s_nop 1
	v_mov_b32_dpp v44, v42 quad_perm:[2,3,0,1] row_mask:0xf bank_mask:0xf
	s_nop 1
	v_mov_b32_dpp v45, v43 quad_perm:[2,3,0,1] row_mask:0xf bank_mask:0xf
	v_lshl_add_u64 v[40:41], v[70:71], 0, s[20:21]
	v_addc_co_u32_e32 v53, vcc, 0, v71, vcc
	s_waitcnt lgkmcnt(1)
	v_add_f32_e32 v42, v42, v44
	s_waitcnt lgkmcnt(0)
	v_add_f32_e32 v43, v43, v45
	s_nop 1
	v_mov_b32_dpp v44, v42 row_half_mirror row_mask:0xf bank_mask:0xf
	s_nop 1
	v_mov_b32_dpp v45, v43 row_half_mirror row_mask:0xf bank_mask:0xf
	v_lshl_add_u64 v[50:51], v[70:71], 0, s[22:23]
	s_waitcnt lgkmcnt(1)
	v_add_f32_e32 v54, v42, v44
	s_waitcnt lgkmcnt(0)
	v_add_f32_e32 v55, v43, v45
	s_nop 1
	v_mov_b32_dpp v56, v55 row_mirror row_mask:0xf bank_mask:0xf
	s_nop 1
	v_mov_b32_dpp v57, v54 row_mirror row_mask:0xf bank_mask:0xf
	global_load_dwordx4 v[42:45], v[38:39], off offset:16
	global_load_dwordx4 v[46:49], v[40:41], off offset:16
	global_load_dwordx4 v[60:63], v[76:77], off
	s_waitcnt lgkmcnt(1)
	v_add_f32_e32 v38, v55, v56
	s_waitcnt lgkmcnt(0)
	v_add_f32_e32 v40, v54, v57
	global_load_dwordx4 v[64:67], v[52:53], off offset:2048
	s_nop 0
	global_load_dwordx4 v[52:55], v[50:51], off offset:16
	v_mov_b32_e32 v39, v38
	s_nop 1
	v_permlane16_swap_b32_e32 v39, v38
	v_mov_b32_e32 v41, v40
	s_nop 1
	v_permlane16_swap_b32_e32 v41, v40
	global_load_dwordx4 v[56:59], v74, s[6:7] offset:16
	global_load_dwordx4 v[68:71], v74, s[6:7]
	s_waitcnt lgkmcnt(1)
	v_add_f32_e32 v38, v38, v39
	v_mov_b32_e32 v39, v38
	s_nop 1
	v_permlane32_swap_b32_e32 v39, v38
	s_waitcnt lgkmcnt(1)
	v_add_f32_e32 v40, v40, v41
	v_mov_b32_e32 v41, v40
	s_nop 1
	v_permlane32_swap_b32_e32 v41, v40
	s_waitcnt lgkmcnt(1)
	v_add_f32_e32 v38, v38, v39
	v_fmamk_f32 v38, v38, 0x3a800000, v219
	v_rsq_f32_e32 v50, v38
	s_waitcnt lgkmcnt(0)
	v_add_f32_e32 v38, v40, v41
	v_fmamk_f32 v38, v38, 0x3a800000, v219
	v_rsq_f32_e32 v76, v38
	v_mul_f32_e32 v38, v50, v89
	v_mul_f32_e32 v39, v50, v93
	v_mul_f32_e32 v38, v18, v38
	v_mul_f32_e32 v39, v19, v39
	v_cvt_pk_bf16_f32 v38, v38, v39
	v_mul_f32_e32 v39, v50, v94
	v_mul_f32_e32 v40, v50, v95
	v_mul_f32_e32 v39, v20, v39
	v_mul_f32_e32 v40, v21, v40
	v_cvt_pk_bf16_f32 v39, v39, v40
	v_mul_f32_e32 v40, v50, v96
	v_mul_f32_e32 v41, v50, v97
	v_mul_f32_e32 v40, v22, v40
	v_mul_f32_e32 v41, v23, v41
	v_cvt_pk_bf16_f32 v40, v40, v41
	v_mul_f32_e32 v41, v50, v90
	v_mul_f32_e32 v51, v50, v104
	v_mul_f32_e32 v41, v24, v41
	v_mul_f32_e32 v51, v25, v51
	v_cvt_pk_bf16_f32 v41, v41, v51
	v_mul_f32_e32 v51, v91, v76
	v_mul_f32_e32 v77, v92, v76
	v_mul_f32_e32 v51, v2, v51
	v_mul_f32_e32 v77, v3, v77
	v_cvt_pk_bf16_f32 v90, v51, v77
	v_mul_f32_e32 v51, v98, v76
	v_mul_f32_e32 v77, v99, v76
	v_mul_f32_e32 v51, v4, v51
	v_mul_f32_e32 v77, v5, v77
	v_cvt_pk_bf16_f32 v91, v51, v77
	v_mul_f32_e32 v51, v100, v76
	v_mul_f32_e32 v77, v101, v76
	v_mul_f32_e32 v51, v6, v51
	v_mul_f32_e32 v77, v7, v77
	v_cvt_pk_bf16_f32 v92, v51, v77
	v_mul_f32_e32 v51, v102, v76
	v_mul_f32_e32 v77, v103, v76
	v_mul_f32_e32 v51, v8, v51
	v_mul_f32_e32 v77, v9, v77
	v_cvt_pk_bf16_f32 v93, v51, v77
	global_store_dwordx4 v74, v[38:41], s[8:9]
	global_store_dwordx4 v74, v[90:93], s[8:9] offset:2048
	v_max3_f32 v77, v75, v84, v83
	v_mul_f32_e32 v38, v50, v107
	v_mul_f32_e32 v39, v50, v108
	v_mul_f32_e32 v38, v26, v38
	v_mul_f32_e32 v39, v27, v39
	v_cvt_pk_bf16_f32 v38, v38, v39
	v_mul_f32_e32 v39, v50, v111
	v_mul_f32_e32 v40, v50, v112
	v_mul_f32_e32 v39, v28, v39
	v_mul_f32_e32 v40, v29, v40
	v_cvt_pk_bf16_f32 v39, v39, v40
	v_mul_f32_e32 v40, v50, v113
	v_mul_f32_e32 v41, v50, v114
	v_sub_f32_e32 v75, v75, v77
	v_sub_f32_e32 v84, v84, v77
	v_mul_f32_e32 v40, v30, v40
	v_mul_f32_e32 v41, v31, v41
	v_mul_f32_e32 v75, 0x3fb8aa3b, v75
	v_mul_f32_e32 v84, 0x3fb8aa3b, v84
	v_sub_f32_e32 v77, v83, v77
	v_cvt_pk_bf16_f32 v40, v40, v41
	v_mul_f32_e32 v41, v50, v115
	v_mul_f32_e32 v50, v50, v116
	v_exp_f32_e32 v75, v75
	v_exp_f32_e32 v84, v84
	v_mul_f32_e32 v77, 0x3fb8aa3b, v77
	v_mul_f32_e32 v41, v32, v41
	v_mul_f32_e32 v50, v33, v50
	v_exp_f32_e32 v77, v77
	v_cvt_pk_bf16_f32 v41, v41, v50
	v_mul_f32_e32 v50, v105, v76
	v_mul_f32_e32 v51, v106, v76
	v_mul_f32_e32 v50, v10, v50
	v_mul_f32_e32 v51, v11, v51
	v_cvt_pk_bf16_f32 v50, v50, v51
	v_add_f32_e32 v51, v75, v84
	v_add_f32_e32 v51, v77, v51
	v_rcp_f32_e32 v51, v51
	v_mul_f32_e32 v83, v109, v76
	v_mul_f32_e32 v90, v12, v83
	s_waitcnt vmcnt(2)
; __device__ __forceinline__ void merge_rows(bf16_t* Z, const float* LSE, const float* ga, const float* gb, int gw, int ngw, int lane) {
;     ...
;         for (int r = 0; r < 2; ++r) {
;             const float mx = fmaxf(l0[r], fmaxf(l1[r], l2[r]));
;             float e0 = __builtin_amdgcn_exp2f((l0[r] - mx) * 1.4426950408889634f), e1 = __builtin_amdgcn_exp2f((l1[r] - mx) * 1.4426950408889634f), e2 = __builtin_amdgcn_exp2f((l2[r] - mx) * 1.4426950408889634f);
;             const float inv = __builtin_amdgcn_rcpf(e0 + e1 + e2); e0 *= inv; e1 *= inv; e2 *= inv;
;             float ob[16], oa[16];
; #pragma unroll
;             for (int h2 = 0; h2 < 2; ++h2)
; #pragma unroll
;                 for (int e = 0; e < 4; ++e) {
;                     ob[8 * h2 + 2 * e] = e0 * bf_lo(q0[r][h2][e]) + e1 * bf_lo(q1[r][h2][e]) + e2 * bf_lo(q2[r][h2][e]); ob[8 * h2 + 2 * e + 1] = e0 * bf_hi(q0[r][h2][e]) + e1 * bf_hi(q1[r][h2][e]) + e2 * bf_hi(q2[r][h2][e]);
;                     oa[8 * h2 + 2 * e] = bf_lo(aa[r][h2][e]); oa[8 * h2 + 2 * e + 1] = bf_hi(aa[r][h2][e]); }
;             float sb = 0.f, sa = 0.f;
; #pragma unroll
;             for (int c = 0; c < 16; ++c) { sb += ob[c] * ob[c]; sa += oa[c] * oa[c]; }
;             sb = wave_sum(sb); sa = wave_sum(sa);
;             const float rb = __builtin_amdgcn_rsqf(sb * (1.f / 1024.f) + EPS), ra = __builtin_amdgcn_rsqf(sa * (1.f / 1024.f) + EPS);
;             bf16_t* mr = Z + (size_t)(m0 + r * ngw) * INW;
;             if (ok[r]) {
; #pragma unroll
;                 for (int h2 = 0; h2 < 2; ++h2) {
;                     const f32x4 ga0 = gav[h2][0], ga1 = gav[h2][1], gb0 = gbv[h2][0], gb1 = gbv[h2][1];
;                     u32x4 wa, wb; const float* A = oa + 8 * h2; const float* B = ob + 8 * h2;
;                     wa.x = pk2(A[0] * ra * ga0[0], A[1] * ra * ga0[1]); wa.y = pk2(A[2] * ra * ga0[2], A[3] * ra * ga0[3]); wa.z = pk2(A[4] * ra * ga1[0], A[5] * ra * ga1[1]); wa.w = pk2(A[6] * ra * ga1[2], A[7] * ra * ga1[3]);
;                     wb.x = pk2(B[0] * rb * gb0[0], B[1] * rb * gb0[1]); wb.y = pk2(B[2] * rb * gb0[2], B[3] * rb * gb0[3]); wb.z = pk2(B[4] * rb * gb1[0], B[5] * rb * gb1[1]); wb.w = pk2(B[6] * rb * gb1[2], B[7] * rb * gb1[3]);
;                     *(u32x4*)(mr + ch0 + 8 * h2) = wa; *(u32x4*)(mr + 1024 + ch0 + 8 * h2) = wb;
	v_lshlrev_b32_e32 v83, 16, v69
	v_mul_f32_e32 v92, v75, v51
	v_mul_f32_e32 v93, v84, v51
	v_lshlrev_b32_e32 v75, 16, v64
	v_mul_f32_e32 v51, v77, v51
	v_lshlrev_b32_e32 v77, 16, v34
	v_mul_f32_e32 v75, v93, v75
	v_fmac_f32_e32 v75, v92, v77
	v_lshlrev_b32_e32 v77, 16, v60
	v_fmac_f32_e32 v75, v51, v77
	v_and_b32_e32 v77, 0xffff0000, v34
	v_and_b32_e32 v34, 0xffff0000, v64
	v_mul_f32_e32 v34, v93, v34
	v_fmac_f32_e32 v34, v92, v77
	v_and_b32_e32 v60, 0xffff0000, v60
	v_fmac_f32_e32 v34, v51, v60
	v_lshlrev_b32_e32 v60, 16, v65
	v_lshlrev_b32_e32 v64, 16, v35
	v_mul_f32_e32 v60, v93, v60
	v_fmac_f32_e32 v60, v92, v64
	v_lshlrev_b32_e32 v64, 16, v61
	v_fmac_f32_e32 v60, v51, v64
	v_and_b32_e32 v64, 0xffff0000, v35
	v_and_b32_e32 v35, 0xffff0000, v65
	v_mul_f32_e32 v35, v93, v35
	v_fmac_f32_e32 v35, v92, v64
	v_and_b32_e32 v61, 0xffff0000, v61
	v_fmac_f32_e32 v35, v51, v61
	v_lshlrev_b32_e32 v61, 16, v66
	v_lshlrev_b32_e32 v64, 16, v36
	v_mul_f32_e32 v61, v93, v61
	v_fmac_f32_e32 v61, v92, v64
	v_lshlrev_b32_e32 v64, 16, v62
	v_fmac_f32_e32 v61, v51, v64
	v_and_b32_e32 v64, 0xffff0000, v66
	v_and_b32_e32 v36, 0xffff0000, v36
	v_mul_f32_e32 v64, v93, v64
	v_fmac_f32_e32 v64, v92, v36
	v_and_b32_e32 v36, 0xffff0000, v62
	v_lshlrev_b32_e32 v62, 16, v67
	v_fmac_f32_e32 v64, v51, v36
	v_lshlrev_b32_e32 v36, 16, v37
	v_mul_f32_e32 v62, v93, v62
	v_fmac_f32_e32 v62, v92, v36
	v_lshlrev_b32_e32 v36, 16, v63
	v_fmac_f32_e32 v62, v51, v36
	v_and_b32_e32 v36, 0xffff0000, v37
	v_and_b32_e32 v37, 0xffff0000, v67
	v_mul_f32_e32 v65, v93, v37
	v_fmac_f32_e32 v65, v92, v36
	v_and_b32_e32 v36, 0xffff0000, v63
	v_fmac_f32_e32 v65, v51, v36
	v_lshlrev_b32_e32 v36, 16, v46
	v_lshlrev_b32_e32 v37, 16, v42
	v_mul_f32_e32 v36, v93, v36
	v_fmac_f32_e32 v36, v92, v37
	v_lshlrev_b32_e32 v37, 16, v52
	v_fmac_f32_e32 v36, v51, v37
	v_and_b32_e32 v37, 0xffff0000, v46
	v_and_b32_e32 v42, 0xffff0000, v42
	v_mul_f32_e32 v37, v93, v37
	v_fmac_f32_e32 v37, v92, v42
	v_and_b32_e32 v42, 0xffff0000, v52
	v_fmac_f32_e32 v37, v51, v42
	v_lshlrev_b32_e32 v42, 16, v47
	v_lshlrev_b32_e32 v46, 16, v43
	v_mul_f32_e32 v42, v93, v42
	v_fmac_f32_e32 v42, v92, v46
	v_lshlrev_b32_e32 v46, 16, v53
	v_fmac_f32_e32 v42, v51, v46
	v_and_b32_e32 v46, 0xffff0000, v43
	v_and_b32_e32 v43, 0xffff0000, v47
	v_mul_f32_e32 v43, v93, v43
	v_fmac_f32_e32 v43, v92, v46
	v_and_b32_e32 v46, 0xffff0000, v53
	v_fmac_f32_e32 v43, v51, v46
	v_lshlrev_b32_e32 v46, 16, v48
	v_lshlrev_b32_e32 v47, 16, v44
	v_mul_f32_e32 v46, v93, v46
	v_fmac_f32_e32 v46, v92, v47
	v_lshlrev_b32_e32 v47, 16, v54
	v_fmac_f32_e32 v46, v51, v47
	v_and_b32_e32 v47, 0xffff0000, v44
	v_and_b32_e32 v44, 0xffff0000, v48
	v_mul_f32_e32 v44, v93, v44
	v_fmac_f32_e32 v44, v92, v47
	v_and_b32_e32 v47, 0xffff0000, v54
	v_fmac_f32_e32 v44, v51, v47
	v_lshlrev_b32_e32 v47, 16, v49
	v_lshlrev_b32_e32 v52, 16, v45
	v_mul_f32_e32 v47, v93, v47
	v_fmac_f32_e32 v47, v92, v52
	v_lshlrev_b32_e32 v52, 16, v55
	v_fmac_f32_e32 v47, v51, v52
	v_and_b32_e32 v52, 0xffff0000, v45
	v_and_b32_e32 v45, 0xffff0000, v49
	v_lshlrev_b32_e32 v77, 16, v68
	v_and_b32_e32 v68, 0xffff0000, v68
	v_mul_f32_e32 v45, v93, v45
	v_fmac_f32_e32 v45, v92, v52
	v_mul_f32_e32 v52, v34, v34
	v_mul_f32_e32 v53, v68, v68
	v_fmac_f32_e32 v52, v75, v75
	v_fmac_f32_e32 v53, v77, v77
	v_and_b32_e32 v69, 0xffff0000, v69
	v_fmac_f32_e32 v52, v60, v60
	v_fmac_f32_e32 v53, v83, v83
	v_lshlrev_b32_e32 v84, 16, v70
	v_fmac_f32_e32 v52, v35, v35
	v_fmac_f32_e32 v53, v69, v69
	v_and_b32_e32 v66, 0xffff0000, v70
	v_fmac_f32_e32 v52, v61, v61
	v_fmac_f32_e32 v53, v84, v84
	v_lshlrev_b32_e32 v89, 16, v71
	v_fmac_f32_e32 v52, v64, v64
	v_fmac_f32_e32 v53, v66, v66
	v_and_b32_e32 v70, 0xffff0000, v71
	v_fmac_f32_e32 v52, v62, v62
	v_fmac_f32_e32 v53, v89, v89
	v_lshlrev_b32_e32 v63, 16, v56
	v_fmac_f32_e32 v52, v65, v65
	v_fmac_f32_e32 v53, v70, v70
	v_and_b32_e32 v56, 0xffff0000, v56
	v_fmac_f32_e32 v52, v36, v36
	v_fmac_f32_e32 v53, v63, v63
	v_lshlrev_b32_e32 v67, 16, v57
	v_fmac_f32_e32 v52, v37, v37
	v_fmac_f32_e32 v53, v56, v56
	v_and_b32_e32 v57, 0xffff0000, v57
	v_fmac_f32_e32 v52, v42, v42
	v_fmac_f32_e32 v53, v67, v67
	v_lshlrev_b32_e32 v54, 16, v58
	v_fmac_f32_e32 v52, v43, v43
	v_fmac_f32_e32 v53, v57, v57
	v_and_b32_e32 v48, 0xffff0000, v58
	v_fmac_f32_e32 v52, v46, v46
	v_fmac_f32_e32 v53, v54, v54
	v_and_b32_e32 v49, 0xffff0000, v55
	v_lshlrev_b32_e32 v55, 16, v59
	v_fmac_f32_e32 v52, v44, v44
	v_fmac_f32_e32 v53, v48, v48
	v_fmac_f32_e32 v45, v51, v49
	v_and_b32_e32 v49, 0xffff0000, v59
	v_fmac_f32_e32 v52, v47, v47
	v_fmac_f32_e32 v53, v55, v55
	v_fmac_f32_e32 v52, v45, v45
	v_fmac_f32_e32 v53, v49, v49
	s_nop 1
	v_mov_b32_dpp v58, v52 quad_perm:[1,0,3,2] row_mask:0xf bank_mask:0xf
	s_nop 1
	v_mov_b32_dpp v59, v53 quad_perm:[1,0,3,2] row_mask:0xf bank_mask:0xf
	v_mul_f32_e32 v71, v88, v76
	v_mul_f32_e32 v91, v110, v76
	v_mul_f32_e32 v87, v87, v76
	s_waitcnt lgkmcnt(1)
	v_add_f32_e32 v52, v52, v58
	s_waitcnt lgkmcnt(0)
	v_add_f32_e32 v53, v53, v59
	s_nop 1
	v_mov_b32_dpp v58, v52 quad_perm:[2,3,0,1] row_mask:0xf bank_mask:0xf
	s_nop 1
	v_mov_b32_dpp v59, v53 quad_perm:[2,3,0,1] row_mask:0xf bank_mask:0xf
	v_mul_f32_e32 v51, v13, v91
	v_mul_f32_e32 v71, v14, v71
	v_mul_f32_e32 v87, v15, v87
	s_waitcnt lgkmcnt(1)
	v_add_f32_e32 v52, v52, v58
	s_waitcnt lgkmcnt(0)
	v_add_f32_e32 v53, v53, v59
	s_nop 1
	v_mov_b32_dpp v58, v52 row_half_mirror row_mask:0xf bank_mask:0xf
	s_nop 1
	v_mov_b32_dpp v59, v53 row_half_mirror row_mask:0xf bank_mask:0xf
	v_cvt_pk_bf16_f32 v51, v90, v51
	v_mul_f32_e32 v85, v85, v76
	s_waitcnt lgkmcnt(1)
	v_add_f32_e32 v58, v52, v58
	s_waitcnt lgkmcnt(0)
	v_add_f32_e32 v53, v53, v59
	s_nop 1
	v_mov_b32_dpp v88, v58 row_mirror row_mask:0xf bank_mask:0xf
	s_nop 1
	v_mov_b32_dpp v59, v53 row_mirror row_mask:0xf bank_mask:0xf
	v_cvt_pk_bf16_f32 v52, v71, v87
	v_mul_f32_e32 v71, v86, v76
	s_waitcnt lgkmcnt(1)
	v_add_f32_e32 v58, v58, v88
	s_waitcnt lgkmcnt(0)
	v_add_f32_e32 v53, v53, v59
	v_mov_b32_e32 v86, v58
	s_nop 1
	v_permlane16_swap_b32_e32 v86, v58
	v_mov_b32_e32 v87, v53
	s_nop 1
	v_permlane16_swap_b32_e32 v87, v53
	v_mul_f32_e32 v88, v16, v71
	s_waitcnt lgkmcnt(1)
	v_add_f32_e32 v58, v58, v86
	s_waitcnt lgkmcnt(0)
	v_add_f32_e32 v71, v53, v87
	v_mov_b32_e32 v59, v58
	s_nop 1
	v_permlane32_swap_b32_e32 v59, v58
	v_mov_b32_e32 v76, v71
	s_nop 1
	v_permlane32_swap_b32_e32 v76, v71
	v_mul_f32_e32 v53, v17, v85
	v_cvt_pk_bf16_f32 v53, v88, v53
	global_store_dwordx4 v74, v[38:41], s[8:9] offset:16
	global_store_dwordx4 v74, v[50:53], s[8:9] offset:2064
	s_cbranch_scc1 .LBB0_207
; __device__ __forceinline__ unsigned pk2(float lo, float hi) { return pg8::cvt_pk_bf16(lo, hi); }
; __device__ __forceinline__ void merge_rows(bf16_t* Z, const float* LSE, const float* ga, const float* gb, int gw, int ngw, int lane) {
;     ...
;             sb = wave_sum(sb); sa = wave_sum(sa);
;             const float rb = __builtin_amdgcn_rsqf(sb * (1.f / 1024.f) + EPS), ra = __builtin_amdgcn_rsqf(sa * (1.f / 1024.f) + EPS);
;             bf16_t* mr = Z + (size_t)(m0 + r * ngw) * INW;
;             if (ok[r]) {
; #pragma unroll
;                 for (int h2 = 0; h2 < 2; ++h2) {
;                     const f32x4 ga0 = gav[h2][0], ga1 = gav[h2][1], gb0 = gbv[h2][0], gb1 = gbv[h2][1];
;                     u32x4 wa, wb; const float* A = oa + 8 * h2; const float* B = ob + 8 * h2;
;                     wa.x = pk2(A[0] * ra * ga0[0], A[1] * ra * ga0[1]); wa.y = pk2(A[2] * ra * ga0[2], A[3] * ra * ga0[3]); wa.z = pk2(A[4] * ra * ga1[0], A[5] * ra * ga1[1]); wa.w = pk2(A[6] * ra * ga1[2], A[7] * ra * ga1[3]);
;                     wb.x = pk2(B[0] * rb * gb0[0], B[1] * rb * gb0[1]); wb.y = pk2(B[2] * rb * gb0[2], B[3] * rb * gb0[3]); wb.z = pk2(B[4] * rb * gb1[0], B[5] * rb * gb1[1]); wb.w = pk2(B[6] * rb * gb1[2], B[7] * rb * gb1[3]);
;                     *(u32x4*)(mr + ch0 + 8 * h2) = wa; *(u32x4*)(mr + 1024 + ch0 + 8 * h2) = wb;
	s_waitcnt lgkmcnt(0)
	v_add_f32_e32 v38, v71, v76
	v_fmamk_f32 v38, v38, 0x3a800000, v219
	v_rsq_f32_e32 v71, v38
	v_add_f32_e32 v38, v58, v59
	v_fmamk_f32 v38, v38, 0x3a800000, v219
	v_rsq_f32_e32 v76, v38
	v_mov_b32_e32 v38, 0x3800
	v_mad_i64_i32 v[58:59], s[6:7], s11, v38, v[72:73]
	v_mul_f32_e32 v38, v71, v77
	v_mul_f32_e32 v39, v71, v68
	v_mul_f32_e32 v38, v18, v38
	v_mul_f32_e32 v39, v19, v39
	v_cvt_pk_bf16_f32 v38, v38, v39
	v_mul_f32_e32 v39, v71, v83
	v_mul_f32_e32 v40, v71, v69
	v_mul_f32_e32 v39, v20, v39
	v_mul_f32_e32 v40, v21, v40
	v_cvt_pk_bf16_f32 v39, v39, v40
	v_mul_f32_e32 v40, v71, v84
	v_mul_f32_e32 v41, v71, v66
	v_mul_f32_e32 v40, v22, v40
	v_mul_f32_e32 v41, v23, v41
	v_cvt_pk_bf16_f32 v40, v40, v41
	v_mul_f32_e32 v41, v71, v89
	v_mul_f32_e32 v50, v71, v70
	v_mul_f32_e32 v41, v24, v41
	v_mul_f32_e32 v50, v25, v50
	v_cvt_pk_bf16_f32 v41, v41, v50
	v_mul_f32_e32 v50, v75, v76
	v_mul_f32_e32 v34, v34, v76
	v_mul_f32_e32 v50, v2, v50
	v_mul_f32_e32 v34, v3, v34
	v_cvt_pk_bf16_f32 v50, v50, v34
	v_mul_f32_e32 v34, v60, v76
	v_mul_f32_e32 v35, v35, v76
	v_mul_f32_e32 v34, v4, v34
	v_mul_f32_e32 v35, v5, v35
	v_cvt_pk_bf16_f32 v51, v34, v35
	v_mul_f32_e32 v34, v61, v76
	v_mul_f32_e32 v35, v64, v76
	v_mul_f32_e32 v34, v6, v34
	v_mul_f32_e32 v35, v7, v35
	v_cvt_pk_bf16_f32 v52, v34, v35
	v_mul_f32_e32 v34, v62, v76
	v_mul_f32_e32 v35, v65, v76
	v_mul_f32_e32 v34, v8, v34
	v_mul_f32_e32 v35, v9, v35
	v_cvt_pk_bf16_f32 v53, v34, v35
	v_mul_f32_e32 v34, v71, v63
	v_mul_f32_e32 v35, v71, v56
	v_mul_f32_e32 v34, v26, v34
	v_mul_f32_e32 v35, v27, v35
	global_store_dwordx4 v[58:59], v[38:41], off
	global_store_dwordx4 v[58:59], v[50:53], off offset:2048
	s_nop 0
	v_cvt_pk_bf16_f32 v38, v34, v35
	v_mul_f32_e32 v34, v71, v67
	v_mul_f32_e32 v35, v71, v57
	v_mul_f32_e32 v34, v28, v34
	v_mul_f32_e32 v35, v29, v35
	v_cvt_pk_bf16_f32 v39, v34, v35
	v_mul_f32_e32 v34, v71, v54
	v_mul_f32_e32 v35, v71, v48
	v_mul_f32_e32 v34, v30, v34
	v_mul_f32_e32 v35, v31, v35
	v_cvt_pk_bf16_f32 v40, v34, v35
	v_mul_f32_e32 v34, v71, v55
	v_mul_f32_e32 v35, v71, v49
	v_mul_f32_e32 v34, v32, v34
	v_mul_f32_e32 v35, v33, v35
	v_cvt_pk_bf16_f32 v41, v34, v35
	v_mul_f32_e32 v34, v36, v76
	v_mul_f32_e32 v35, v37, v76
	v_mul_f32_e32 v34, v10, v34
	v_mul_f32_e32 v35, v11, v35
	v_cvt_pk_bf16_f32 v34, v34, v35
	v_mul_f32_e32 v35, v42, v76
	v_mul_f32_e32 v36, v43, v76
	v_mul_f32_e32 v35, v12, v35
	v_mul_f32_e32 v36, v13, v36
	v_cvt_pk_bf16_f32 v35, v35, v36
	v_mul_f32_e32 v36, v46, v76
	v_mul_f32_e32 v37, v44, v76
	v_mul_f32_e32 v36, v14, v36
	v_mul_f32_e32 v37, v15, v37
	v_cvt_pk_bf16_f32 v36, v36, v37
	v_mul_f32_e32 v37, v47, v76
	v_mul_f32_e32 v37, v16, v37
	v_mul_f32_e32 v42, v45, v76
	v_mul_f32_e32 v42, v17, v42
	v_cvt_pk_bf16_f32 v37, v37, v42
	global_store_dwordx4 v[58:59], v[38:41], off offset:16
	global_store_dwordx4 v[58:59], v[34:37], off offset:2064
	s_branch .LBB0_207

;     __device__ __forceinline__ void operator()(const f32x4 (&acc)[2][2][4][2], const Unit& u, int wr, int wc, int fr, int fq, const float (&pre)[8]) const {
;     ...
;                 for (int m = 0; m < 4; ++m) csv[ai][m] = *(const u32x4*)((const unsigned*)rope + (size_t)((row0 + ai * HALF + m * 16) & 4095) * 64 + 16 * wc + 4 * fq);
;             asm volatile("" ::: "memory");
; #pragma unroll
;             for (int ai = 0; ai < 2; ++ai)
; #pragma unroll
;                 for (int m = 0; m < 4; ++m) { const float rs = __builtin_amdgcn_rsqf(pre[ai * 4 + m] * (1.f / 2048.f) + 1e-6f); rsv[ai][m] = rs;
; #pragma unroll
;                     for (int bj = 0; bj < 2; ++bj) { const f32x4 a = acc[ai][bj][m][0] * rs, b = acc[ai][bj][m][1] * rs;
;                         float ss = ((a[0] * a[0] + a[1] * a[1]) + (a[2] * a[2] + a[3] * a[3])) + ((b[0] * b[0] + b[1] * b[1]) + (b[2] * b[2] + b[3] * b[3]));
;                         ss += __shfl_xor(ss, 16); ss += __shfl_xor(ss, 32);
;                         if (fq == 0) xl[((ai * HALF + wr * 64 + m * 16 + fr) * 2 + bj) * 4 + wc] = ss; } }
.LBB0_478:
	v_lshlrev_b32_e32 v130, 8, v237
	v_and_b32_e32 v196, 0xfcf00, v130
	v_lshl_add_u64 v[130:131], v[178:179], 0, v[196:197]
	v_add_co_u32_e32 v132, vcc, 0x1000, v130
	s_movk_i32 s0, 0x3000
	s_nop 0
	v_addc_co_u32_e32 v133, vcc, 0, v131, vcc
	global_load_dwordx4 v[166:169], v[130:131], off
	global_load_dwordx4 v[162:165], v[132:133], off
	v_add_co_u32_e32 v132, vcc, 0x2000, v130
	v_and_b32_e32 v193, 64, v222
	s_nop 0
	v_addc_co_u32_e32 v133, vcc, 0, v131, vcc
	v_add_co_u32_e32 v130, vcc, 0x3000, v130
	v_add_u32_e32 v193, 64, v193
	s_nop 0
	v_addc_co_u32_e32 v131, vcc, 0, v131, vcc
	global_load_dwordx4 v[158:161], v[132:133], off
	global_load_dwordx4 v[154:157], v[130:131], off
	v_lshl_add_u32 v130, v237, 6, v254
	v_and_b32_e32 v130, 0x3f3c0, v130
	v_lshlrev_b32_e32 v196, 2, v130
	v_lshl_add_u64 v[130:131], v[178:179], 0, v[196:197]
	v_add_co_u32_e32 v132, vcc, s85, v130
	v_pk_mul_f32 v[198:199], v[192:193], v[128:129] op_sel_hi:[0,1]
	s_nop 0
	v_addc_co_u32_e32 v133, vcc, 0, v131, vcc
	global_load_dwordx4 v[138:141], v[132:133], off offset:-4096
	global_load_dwordx4 v[134:137], v[132:133], off
	v_add_co_u32_e32 v132, vcc, s0, v130
	v_pk_mul_f32 v[200:201], v[192:193], v[126:127] op_sel_hi:[0,1]
	s_nop 0
	v_addc_co_u32_e32 v133, vcc, 0, v131, vcc
	global_load_dwordx4 v[150:153], v[130:131], off
	s_nop 0
	global_load_dwordx4 v[130:133], v[132:133], off
	v_mul_f32_e32 v195, v201, v201
	v_mul_f32_e32 v196, v199, v199
	v_pk_mul_f32 v[202:203], v[192:193], v[124:125] op_sel_hi:[0,1]
	v_pk_mul_f32 v[204:205], v[192:193], v[122:123] op_sel_hi:[0,1]
	v_fmac_f32_e32 v195, v200, v200
	v_fmac_f32_e32 v196, v198, v198
	v_xor_b32_e32 v148, 16, v222
	v_add_f32_e32 v195, v195, v196
	v_mul_f32_e32 v196, v205, v205
	v_mul_f32_e32 v198, v203, v203
	v_cmp_lt_i32_e32 vcc, v148, v193
	v_fmac_f32_e32 v196, v204, v204
	v_fmac_f32_e32 v198, v202, v202
	v_cndmask_b32_e32 v148, v222, v148, vcc
	v_add_f32_e32 v196, v196, v198
	v_lshlrev_b32_e32 v148, 2, v148
	v_add_f32_e32 v196, v195, v196
	v_mov_b32_e32 v198, v196
	s_nop 1
	v_permlane16_swap_b32_e32 v198, v196
	v_xor_b32_e32 v195, 32, v222
	v_cmp_lt_i32_e32 vcc, v195, v193
	s_nop 1
	v_cndmask_b32_e32 v193, v222, v195, vcc
	v_lshlrev_b32_e32 v195, 2, v193
	s_waitcnt lgkmcnt(0)
	v_add_f32_e32 v193, v196, v198
	v_mov_b32_e32 v196, v193
	s_nop 1
	v_permlane32_swap_b32_e32 v196, v193
	s_and_saveexec_b64 s[0:1], s[6:7]
	s_cbranch_execz .LBB0_480
	s_waitcnt lgkmcnt(0)
	v_add_f32_e32 v193, v193, v196
	ds_write_b32 v227, v193
.LBB0_480:
	s_or_b64 exec, exec, s[0:1]
	v_mov_b32_e32 v193, v192
	v_mov_b32_e32 v198, v192
	v_mov_b32_e32 v199, v192
	v_pk_mul_f32 v[200:201], v[198:199], v[120:121]
	v_pk_mul_f32 v[202:203], v[192:193], v[118:119]
	v_pk_mul_f32 v[204:205], v[192:193], v[114:115]
	v_mul_f32_e32 v193, v203, v203
	s_waitcnt lgkmcnt(0)
	v_mul_f32_e32 v196, v201, v201
	v_pk_mul_f32 v[198:199], v[198:199], v[116:117]
	v_fmac_f32_e32 v193, v202, v202
	v_fmac_f32_e32 v196, v200, v200
	v_add_f32_e32 v193, v193, v196
	v_mul_f32_e32 v196, v205, v205
	v_mul_f32_e32 v199, v199, v199
	v_fmac_f32_e32 v196, v204, v204
	v_fmac_f32_e32 v199, v198, v198
	v_add_f32_e32 v196, v196, v199
	v_add_f32_e32 v193, v193, v196
	v_mov_b32_e32 v196, v193
	s_nop 1
	v_permlane16_swap_b32_e32 v196, v193
	s_waitcnt lgkmcnt(0)
	v_add_f32_e32 v193, v193, v196
	v_mov_b32_e32 v196, v193
	s_nop 1
	v_permlane32_swap_b32_e32 v196, v193
	s_and_saveexec_b64 s[0:1], s[6:7]
	s_cbranch_execz .LBB0_482
	s_waitcnt lgkmcnt(0)
	v_add_f32_e32 v193, v193, v196
	ds_write_b32 v227, v193 offset:16
.LBB0_482:
	s_or_b64 exec, exec, s[0:1]
	v_fmamk_f32 v149, v149, 0x3a000000, v219
	v_rsq_f32_e32 v216, v149
	s_nop 0
	v_pk_mul_f32 v[198:199], v[216:217], v[112:113] op_sel_hi:[0,1]
	v_pk_mul_f32 v[200:201], v[216:217], v[110:111] op_sel_hi:[0,1]
	v_mul_f32_e32 v149, v201, v201
	v_mul_f32_e32 v193, v199, v199
	v_pk_mul_f32 v[202:203], v[216:217], v[108:109] op_sel_hi:[0,1]
	v_pk_mul_f32 v[204:205], v[216:217], v[106:107] op_sel_hi:[0,1]
	v_fmac_f32_e32 v149, v200, v200
	v_fmac_f32_e32 v193, v198, v198
	v_add_f32_e32 v149, v149, v193
	v_mul_f32_e32 v193, v205, v205
	s_waitcnt lgkmcnt(0)
	v_mul_f32_e32 v196, v203, v203
	v_fmac_f32_e32 v193, v204, v204
	v_fmac_f32_e32 v196, v202, v202
	v_add_f32_e32 v193, v193, v196
	v_add_f32_e32 v149, v149, v193
	v_mov_b32_e32 v193, v149
	s_nop 1
	v_permlane16_swap_b32_e32 v193, v149
	s_waitcnt lgkmcnt(0)
	v_add_f32_e32 v149, v149, v193
	v_mov_b32_e32 v193, v149
	s_nop 1
	v_permlane32_swap_b32_e32 v193, v149
	s_and_saveexec_b64 s[0:1], s[6:7]
	s_cbranch_execz .LBB0_484
	s_waitcnt lgkmcnt(0)
	v_add_f32_e32 v149, v149, v193
	ds_write_b32 v228, v149
.LBB0_484:
	s_or_b64 exec, exec, s[0:1]
	v_mov_b32_e32 v217, v216
	v_mov_b32_e32 v198, v216
	v_mov_b32_e32 v199, v216
	v_pk_mul_f32 v[200:201], v[198:199], v[104:105]
	v_pk_mul_f32 v[202:203], v[216:217], v[102:103]
	s_waitcnt lgkmcnt(0)
	v_mul_f32_e32 v193, v201, v201
	v_mul_f32_e32 v149, v203, v203
	v_pk_mul_f32 v[198:199], v[198:199], v[100:101]
	v_pk_mul_f32 v[204:205], v[216:217], v[98:99]
	v_fmac_f32_e32 v149, v202, v202
	v_fmac_f32_e32 v193, v200, v200
	v_add_f32_e32 v149, v149, v193
	v_mul_f32_e32 v193, v205, v205
	v_mul_f32_e32 v196, v199, v199
	v_fmac_f32_e32 v193, v204, v204
	v_fmac_f32_e32 v196, v198, v198
	v_add_f32_e32 v193, v193, v196
	v_add_f32_e32 v149, v149, v193
	v_mov_b32_e32 v193, v149
	s_nop 1
	v_permlane16_swap_b32_e32 v193, v149
	s_waitcnt lgkmcnt(0)
	v_add_f32_e32 v149, v149, v193
	v_mov_b32_e32 v193, v149
	s_nop 1
	v_permlane32_swap_b32_e32 v193, v149
	s_and_saveexec_b64 s[0:1], s[6:7]
	s_cbranch_execz .LBB0_486
	s_waitcnt lgkmcnt(0)
	v_add_f32_e32 v149, v149, v193
	ds_write_b32 v228, v149 offset:16
;     __device__ __forceinline__ void operator()(const f32x4 (&acc)[2][2][4][2], const Unit& u, int wr, int wc, int fr, int fq, const float (&pre)[8]) const {
;     ...
;                 for (int m = 0; m < 4; ++m) { const float rs = __builtin_amdgcn_rsqf(pre[ai * 4 + m] * (1.f / 2048.f) + 1e-6f); rsv[ai][m] = rs;
; #pragma unroll
;                     for (int bj = 0; bj < 2; ++bj) { const f32x4 a = acc[ai][bj][m][0] * rs, b = acc[ai][bj][m][1] * rs;
;                         float ss = ((a[0] * a[0] + a[1] * a[1]) + (a[2] * a[2] + a[3] * a[3])) + ((b[0] * b[0] + b[1] * b[1]) + (b[2] * b[2] + b[3] * b[3]));
;                         ss += __shfl_xor(ss, 16); ss += __shfl_xor(ss, 32);
;                         if (fq == 0) xl[((ai * HALF + wr * 64 + m * 16 + fr) * 2 + bj) * 4 + wc] = ss; } }
.LBB0_486:
	s_or_b64 exec, exec, s[0:1]
	v_fmamk_f32 v146, v146, 0x3a000000, v219
	v_rsq_f32_e32 v214, v146
	s_nop 0
	v_pk_mul_f32 v[198:199], v[214:215], v[96:97] op_sel_hi:[0,1]
	v_pk_mul_f32 v[200:201], v[214:215], v[94:95] op_sel_hi:[0,1]
	v_mul_f32_e32 v146, v201, v201
	v_mul_f32_e32 v149, v199, v199
	v_pk_mul_f32 v[202:203], v[214:215], v[92:93] op_sel_hi:[0,1]
	v_pk_mul_f32 v[204:205], v[214:215], v[90:91] op_sel_hi:[0,1]
	v_fmac_f32_e32 v146, v200, v200
	v_fmac_f32_e32 v149, v198, v198
	v_add_f32_e32 v146, v146, v149
	v_mul_f32_e32 v149, v205, v205
	s_waitcnt lgkmcnt(0)
	v_mul_f32_e32 v193, v203, v203
	v_fmac_f32_e32 v149, v204, v204
	v_fmac_f32_e32 v193, v202, v202
	v_add_f32_e32 v149, v149, v193
	v_add_f32_e32 v146, v146, v149
	v_mov_b32_e32 v149, v146
	s_nop 1
	v_permlane16_swap_b32_e32 v149, v146
	s_waitcnt lgkmcnt(0)
	v_add_f32_e32 v146, v146, v149
	v_mov_b32_e32 v149, v146
	s_nop 1
	v_permlane32_swap_b32_e32 v149, v146
	s_and_saveexec_b64 s[0:1], s[6:7]
	s_cbranch_execz .LBB0_488
	s_waitcnt lgkmcnt(0)
	v_add_f32_e32 v146, v146, v149
	ds_write_b32 v229, v146
.LBB0_488:
	s_or_b64 exec, exec, s[0:1]
	v_mov_b32_e32 v215, v214
	v_mov_b32_e32 v198, v214
	v_mov_b32_e32 v199, v214
	v_pk_mul_f32 v[200:201], v[198:199], v[88:89]
	v_pk_mul_f32 v[202:203], v[214:215], v[86:87]
	s_waitcnt lgkmcnt(0)
	v_mul_f32_e32 v149, v201, v201
	v_mul_f32_e32 v146, v203, v203
	v_pk_mul_f32 v[198:199], v[198:199], v[84:85]
	v_pk_mul_f32 v[204:205], v[214:215], v[82:83]
	v_fmac_f32_e32 v146, v202, v202
	v_fmac_f32_e32 v149, v200, v200
	v_add_f32_e32 v146, v146, v149
	v_mul_f32_e32 v149, v205, v205
	v_mul_f32_e32 v193, v199, v199
	v_fmac_f32_e32 v149, v204, v204
	v_fmac_f32_e32 v193, v198, v198
	v_add_f32_e32 v149, v149, v193
	v_add_f32_e32 v146, v146, v149
	v_mov_b32_e32 v149, v146
	s_nop 1
	v_permlane16_swap_b32_e32 v149, v146
	s_waitcnt lgkmcnt(0)
	v_add_f32_e32 v146, v146, v149
	v_mov_b32_e32 v149, v146
	s_nop 1
	v_permlane32_swap_b32_e32 v149, v146
	s_and_saveexec_b64 s[0:1], s[6:7]
	s_cbranch_execz .LBB0_490
	s_waitcnt lgkmcnt(0)
	v_add_f32_e32 v146, v146, v149
	ds_write_b32 v229, v146 offset:16
.LBB0_490:
	s_or_b64 exec, exec, s[0:1]
	v_fmamk_f32 v146, v147, 0x3a000000, v219
	v_rsq_f32_e32 v212, v146
	s_nop 0
	v_pk_mul_f32 v[146:147], v[212:213], v[80:81] op_sel_hi:[0,1]
	v_pk_mul_f32 v[198:199], v[212:213], v[78:79] op_sel_hi:[0,1]
	s_waitcnt lgkmcnt(0)
	v_mul_f32_e32 v149, v199, v199
	v_mul_f32_e32 v147, v147, v147
	v_pk_mul_f32 v[200:201], v[212:213], v[76:77] op_sel_hi:[0,1]
	v_pk_mul_f32 v[202:203], v[212:213], v[74:75] op_sel_hi:[0,1]
	v_fmac_f32_e32 v149, v198, v198
	v_fmac_f32_e32 v147, v146, v146
	v_add_f32_e32 v146, v149, v147
	v_mul_f32_e32 v147, v203, v203
	v_mul_f32_e32 v149, v201, v201
	v_fmac_f32_e32 v147, v202, v202
	v_fmac_f32_e32 v149, v200, v200
	v_add_f32_e32 v147, v147, v149
	v_add_f32_e32 v146, v146, v147
	v_mov_b32_e32 v147, v146
	s_nop 1
	v_permlane16_swap_b32_e32 v147, v146
	s_waitcnt lgkmcnt(0)
	v_add_f32_e32 v146, v146, v147
	v_mov_b32_e32 v147, v146
	s_nop 1
	v_permlane32_swap_b32_e32 v147, v146
	s_and_saveexec_b64 s[0:1], s[6:7]
	s_cbranch_execz .LBB0_492
	s_waitcnt lgkmcnt(0)
	v_add_f32_e32 v146, v146, v147
	ds_write_b32 v230, v146
.LBB0_492:
	s_or_b64 exec, exec, s[0:1]
	v_mov_b32_e32 v213, v212
	v_mov_b32_e32 v146, v212
	s_waitcnt lgkmcnt(0)
	v_mov_b32_e32 v147, v212
	v_pk_mul_f32 v[198:199], v[146:147], v[72:73]
	v_pk_mul_f32 v[200:201], v[212:213], v[70:71]
	v_mul_f32_e32 v193, v199, v199
	v_mul_f32_e32 v149, v201, v201
	v_pk_mul_f32 v[146:147], v[146:147], v[68:69]
	v_pk_mul_f32 v[202:203], v[212:213], v[66:67]
	v_fmac_f32_e32 v149, v200, v200
	v_fmac_f32_e32 v193, v198, v198
	v_add_f32_e32 v149, v149, v193
	v_mul_f32_e32 v193, v203, v203
	v_mul_f32_e32 v147, v147, v147
	v_fmac_f32_e32 v193, v202, v202
	v_fmac_f32_e32 v147, v146, v146
	v_add_f32_e32 v146, v193, v147
	v_add_f32_e32 v146, v149, v146
	v_mov_b32_e32 v147, v146
	s_nop 1
	v_permlane16_swap_b32_e32 v147, v146
	s_waitcnt lgkmcnt(0)
	v_add_f32_e32 v146, v146, v147
	v_mov_b32_e32 v147, v146
	s_nop 1
	v_permlane32_swap_b32_e32 v147, v146
	s_and_saveexec_b64 s[0:1], s[6:7]
	s_cbranch_execz .LBB0_494
	s_waitcnt lgkmcnt(0)
	v_add_f32_e32 v146, v146, v147
	ds_write_b32 v230, v146 offset:16
.LBB0_494:
	s_or_b64 exec, exec, s[0:1]
	v_fmamk_f32 v144, v144, 0x3a000000, v219
	v_rsq_f32_e32 v210, v144
	s_waitcnt lgkmcnt(0)
	v_pk_mul_f32 v[146:147], v[210:211], v[64:65] op_sel_hi:[0,1]
	v_pk_mul_f32 v[198:199], v[210:211], v[62:63] op_sel_hi:[0,1]
	v_mul_f32_e32 v144, v199, v199
	v_mul_f32_e32 v147, v147, v147
	v_pk_mul_f32 v[200:201], v[210:211], v[60:61] op_sel_hi:[0,1]
	v_pk_mul_f32 v[202:203], v[210:211], v[58:59] op_sel_hi:[0,1]
	v_fmac_f32_e32 v144, v198, v198
	v_fmac_f32_e32 v147, v146, v146
	v_add_f32_e32 v144, v144, v147
	v_mul_f32_e32 v146, v203, v203
	v_mul_f32_e32 v147, v201, v201
	v_fmac_f32_e32 v146, v202, v202
	v_fmac_f32_e32 v147, v200, v200
	v_add_f32_e32 v146, v146, v147
	v_add_f32_e32 v144, v144, v146
	v_mov_b32_e32 v146, v144
	s_nop 1
	v_permlane16_swap_b32_e32 v146, v144
	s_waitcnt lgkmcnt(0)
	v_add_f32_e32 v144, v144, v146
	v_mov_b32_e32 v146, v144
	s_nop 1
	v_permlane32_swap_b32_e32 v146, v144
	s_and_saveexec_b64 s[0:1], s[6:7]
	s_cbranch_execz .LBB0_496
	s_waitcnt lgkmcnt(0)
	v_add_f32_e32 v144, v144, v146
	ds_write_b32 v231, v144
;     __device__ __forceinline__ void operator()(const f32x4 (&acc)[2][2][4][2], const Unit& u, int wr, int wc, int fr, int fq, const float (&pre)[8]) const {
;     ...
;                 for (int m = 0; m < 4; ++m) { const float rs = __builtin_amdgcn_rsqf(pre[ai * 4 + m] * (1.f / 2048.f) + 1e-6f); rsv[ai][m] = rs;
; #pragma unroll
;                     for (int bj = 0; bj < 2; ++bj) { const f32x4 a = acc[ai][bj][m][0] * rs, b = acc[ai][bj][m][1] * rs;
;                         float ss = ((a[0] * a[0] + a[1] * a[1]) + (a[2] * a[2] + a[3] * a[3])) + ((b[0] * b[0] + b[1] * b[1]) + (b[2] * b[2] + b[3] * b[3]));
;                         ss += __shfl_xor(ss, 16); ss += __shfl_xor(ss, 32);
;                         if (fq == 0) xl[((ai * HALF + wr * 64 + m * 16 + fr) * 2 + bj) * 4 + wc] = ss; } }
.LBB0_496:
	s_or_b64 exec, exec, s[0:1]
	v_mov_b32_e32 v211, v210
	s_waitcnt lgkmcnt(0)
	v_mov_b32_e32 v146, v210
	v_mov_b32_e32 v147, v210
	v_pk_mul_f32 v[198:199], v[146:147], v[56:57]
	v_pk_mul_f32 v[200:201], v[210:211], v[54:55]
	v_mul_f32_e32 v149, v199, v199
	v_mul_f32_e32 v144, v201, v201
	v_pk_mul_f32 v[146:147], v[146:147], v[52:53]
	v_pk_mul_f32 v[202:203], v[210:211], v[50:51]
	v_fmac_f32_e32 v144, v200, v200
	v_fmac_f32_e32 v149, v198, v198
	v_add_f32_e32 v144, v144, v149
	v_mul_f32_e32 v149, v203, v203
	v_mul_f32_e32 v147, v147, v147
	v_fmac_f32_e32 v149, v202, v202
	v_fmac_f32_e32 v147, v146, v146
	v_add_f32_e32 v146, v149, v147
	v_add_f32_e32 v144, v144, v146
	v_mov_b32_e32 v146, v144
	s_nop 1
	v_permlane16_swap_b32_e32 v146, v144
	s_waitcnt lgkmcnt(0)
	v_add_f32_e32 v144, v144, v146
	v_mov_b32_e32 v146, v144
	s_nop 1
	v_permlane32_swap_b32_e32 v146, v144
	s_and_saveexec_b64 s[0:1], s[6:7]
	s_cbranch_execz .LBB0_498
	s_waitcnt lgkmcnt(0)
	v_add_f32_e32 v144, v144, v146
	ds_write_b32 v231, v144 offset:16
.LBB0_498:
	s_or_b64 exec, exec, s[0:1]
	v_fmamk_f32 v144, v145, 0x3a000000, v219
	v_rsq_f32_e32 v206, v144
	s_nop 0
	v_pk_mul_f32 v[144:145], v[206:207], v[48:49] op_sel_hi:[0,1]
	s_waitcnt lgkmcnt(0)
	v_pk_mul_f32 v[146:147], v[206:207], v[46:47] op_sel_hi:[0,1]
	v_mul_f32_e32 v147, v147, v147
	v_mul_f32_e32 v145, v145, v145
	v_pk_mul_f32 v[198:199], v[206:207], v[44:45] op_sel_hi:[0,1]
	v_pk_mul_f32 v[200:201], v[206:207], v[42:43] op_sel_hi:[0,1]
	v_fmac_f32_e32 v147, v146, v146
	v_fmac_f32_e32 v145, v144, v144
	v_add_f32_e32 v144, v147, v145
	v_mul_f32_e32 v145, v201, v201
	v_mul_f32_e32 v146, v199, v199
	v_fmac_f32_e32 v145, v200, v200
	v_fmac_f32_e32 v146, v198, v198
	v_add_f32_e32 v145, v145, v146
	v_add_f32_e32 v144, v144, v145
	v_mov_b32_e32 v145, v144
	s_nop 1
	v_permlane16_swap_b32_e32 v145, v144
	s_waitcnt lgkmcnt(0)
	v_add_f32_e32 v144, v144, v145
	v_mov_b32_e32 v145, v144
	s_nop 1
	v_permlane32_swap_b32_e32 v145, v144
	s_and_saveexec_b64 s[0:1], s[6:7]
	s_cbranch_execz .LBB0_500
	s_waitcnt lgkmcnt(0)
	v_add_f32_e32 v144, v144, v145
	ds_write_b32 v232, v144
.LBB0_500:
	s_or_b64 exec, exec, s[0:1]
	v_mov_b32_e32 v207, v206
	v_mov_b32_e32 v144, v206
	s_waitcnt lgkmcnt(0)
	v_mov_b32_e32 v145, v206
	v_pk_mul_f32 v[146:147], v[144:145], v[40:41]
	v_pk_mul_f32 v[198:199], v[206:207], v[38:39]
	v_mul_f32_e32 v147, v147, v147
	v_mul_f32_e32 v149, v199, v199
	v_pk_mul_f32 v[144:145], v[144:145], v[36:37]
	v_pk_mul_f32 v[200:201], v[206:207], v[34:35]
	v_fmac_f32_e32 v149, v198, v198
	v_fmac_f32_e32 v147, v146, v146
	v_add_f32_e32 v146, v149, v147
	v_mul_f32_e32 v147, v201, v201
	v_mul_f32_e32 v145, v145, v145
	v_fmac_f32_e32 v147, v200, v200
	v_fmac_f32_e32 v145, v144, v144
	v_add_f32_e32 v144, v147, v145
	v_add_f32_e32 v144, v146, v144
	v_mov_b32_e32 v145, v144
	s_nop 1
	v_permlane16_swap_b32_e32 v145, v144
	s_waitcnt lgkmcnt(0)
	v_add_f32_e32 v144, v144, v145
	v_mov_b32_e32 v145, v144
	s_nop 1
	v_permlane32_swap_b32_e32 v145, v144
	s_and_saveexec_b64 s[0:1], s[6:7]
	s_cbranch_execz .LBB0_502
	s_waitcnt lgkmcnt(0)
	v_add_f32_e32 v144, v144, v145
	ds_write_b32 v232, v144 offset:16
;     __device__ __forceinline__ void operator()(const f32x4 (&acc)[2][2][4][2], const Unit& u, int wr, int wc, int fr, int fq, const float (&pre)[8]) const {
;     ...
;                 for (int m = 0; m < 4; ++m) { const float rs = __builtin_amdgcn_rsqf(pre[ai * 4 + m] * (1.f / 2048.f) + 1e-6f); rsv[ai][m] = rs;
; #pragma unroll
;                     for (int bj = 0; bj < 2; ++bj) { const f32x4 a = acc[ai][bj][m][0] * rs, b = acc[ai][bj][m][1] * rs;
;                         float ss = ((a[0] * a[0] + a[1] * a[1]) + (a[2] * a[2] + a[3] * a[3])) + ((b[0] * b[0] + b[1] * b[1]) + (b[2] * b[2] + b[3] * b[3]));
;                         ss += __shfl_xor(ss, 16); ss += __shfl_xor(ss, 32);
;                         if (fq == 0) xl[((ai * HALF + wr * 64 + m * 16 + fr) * 2 + bj) * 4 + wc] = ss; } }
.LBB0_502:
	s_or_b64 exec, exec, s[0:1]
	v_fmamk_f32 v142, v142, 0x3a000000, v219
	v_rsq_f32_e32 v204, v142
	s_waitcnt lgkmcnt(0)
	v_pk_mul_f32 v[144:145], v[204:205], v[32:33] op_sel_hi:[0,1]
	v_pk_mul_f32 v[146:147], v[204:205], v[30:31] op_sel_hi:[0,1]
	v_mul_f32_e32 v142, v147, v147
	v_mul_f32_e32 v145, v145, v145
	v_pk_mul_f32 v[198:199], v[204:205], v[28:29] op_sel_hi:[0,1]
	v_pk_mul_f32 v[200:201], v[204:205], v[26:27] op_sel_hi:[0,1]
	v_fmac_f32_e32 v142, v146, v146
	v_fmac_f32_e32 v145, v144, v144
	v_add_f32_e32 v142, v142, v145
	v_mul_f32_e32 v144, v201, v201
	v_mul_f32_e32 v145, v199, v199
	v_fmac_f32_e32 v144, v200, v200
	v_fmac_f32_e32 v145, v198, v198
	v_add_f32_e32 v144, v144, v145
	v_add_f32_e32 v142, v142, v144
	v_mov_b32_e32 v144, v142
	s_nop 1
	v_permlane16_swap_b32_e32 v144, v142
	s_waitcnt lgkmcnt(0)
	v_add_f32_e32 v142, v142, v144
	v_mov_b32_e32 v144, v142
	s_nop 1
	v_permlane32_swap_b32_e32 v144, v142
	s_and_saveexec_b64 s[0:1], s[6:7]
	s_cbranch_execz .LBB0_504
	s_waitcnt lgkmcnt(0)
	v_add_f32_e32 v142, v142, v144
	ds_write_b32 v233, v142
.LBB0_504:
	s_or_b64 exec, exec, s[0:1]
	s_waitcnt lgkmcnt(0)
	v_mov_b32_e32 v144, v204
	v_mov_b32_e32 v145, v204
	v_mov_b32_e32 v205, v204
	v_pk_mul_f32 v[146:147], v[144:145], v[24:25]
	v_pk_mul_f32 v[198:199], v[204:205], v[22:23]
	v_pk_mul_f32 v[144:145], v[144:145], v[20:21]
	v_pk_mul_f32 v[200:201], v[204:205], v[18:19]
	v_mul_f32_e32 v147, v147, v147
	v_mul_f32_e32 v142, v199, v199
	v_fmac_f32_e32 v147, v146, v146
	v_mul_f32_e32 v146, v201, v201
	v_mul_f32_e32 v145, v145, v145
	v_fmac_f32_e32 v142, v198, v198
	v_fmac_f32_e32 v146, v200, v200
	v_fmac_f32_e32 v145, v144, v144
	v_add_f32_e32 v142, v142, v147
	v_add_f32_e32 v144, v146, v145
	v_add_f32_e32 v142, v142, v144
	v_mov_b32_e32 v144, v142
	s_nop 1
	v_permlane16_swap_b32_e32 v144, v142
	s_waitcnt lgkmcnt(0)
	v_add_f32_e32 v142, v142, v144
	v_mov_b32_e32 v144, v142
	s_nop 1
	v_permlane32_swap_b32_e32 v144, v142
	s_and_saveexec_b64 s[0:1], s[6:7]
	s_cbranch_execz .LBB0_506
	s_waitcnt lgkmcnt(0)
	v_add_f32_e32 v142, v142, v144
	ds_write_b32 v233, v142 offset:16
.LBB0_506:
	s_or_b64 exec, exec, s[0:1]
	v_fmamk_f32 v142, v143, 0x3a000000, v219
	v_rsq_f32_e32 v202, v142
	s_nop 0
	v_pk_mul_f32 v[142:143], v[202:203], v[16:17] op_sel_hi:[0,1]
	s_waitcnt lgkmcnt(0)
	v_pk_mul_f32 v[144:145], v[202:203], v[14:15] op_sel_hi:[0,1]
	v_mul_f32_e32 v145, v145, v145
	v_mul_f32_e32 v143, v143, v143
	v_pk_mul_f32 v[146:147], v[202:203], v[12:13] op_sel_hi:[0,1]
	v_pk_mul_f32 v[198:199], v[202:203], v[10:11] op_sel_hi:[0,1]
	v_fmac_f32_e32 v145, v144, v144
	v_fmac_f32_e32 v143, v142, v142
	v_add_f32_e32 v142, v145, v143
	v_mul_f32_e32 v143, v199, v199
	v_mul_f32_e32 v144, v147, v147
	v_fmac_f32_e32 v143, v198, v198
	v_fmac_f32_e32 v144, v146, v146
	v_add_f32_e32 v143, v143, v144
	v_add_f32_e32 v142, v142, v143
	v_mov_b32_e32 v143, v142
	s_nop 1
	v_permlane16_swap_b32_e32 v143, v142
	s_waitcnt lgkmcnt(0)
	v_add_f32_e32 v142, v142, v143
	v_mov_b32_e32 v143, v142
	s_nop 1
	v_permlane32_swap_b32_e32 v143, v142
	s_and_saveexec_b64 s[0:1], s[6:7]
	s_cbranch_execz .LBB0_508
	s_waitcnt lgkmcnt(0)
	v_add_f32_e32 v142, v142, v143
	ds_write_b32 v234, v142
.LBB0_508:
	s_or_b64 exec, exec, s[0:1]
	v_mov_b32_e32 v203, v202
	v_mov_b32_e32 v142, v202
	s_waitcnt lgkmcnt(0)
	v_mov_b32_e32 v143, v202
	v_pk_mul_f32 v[144:145], v[142:143], v[8:9]
	v_pk_mul_f32 v[146:147], v[202:203], v[6:7]
	v_mul_f32_e32 v145, v145, v145
	v_mul_f32_e32 v147, v147, v147
	v_pk_mul_f32 v[142:143], v[142:143], v[4:5]
	v_pk_mul_f32 v[198:199], v[202:203], v[2:3]
	v_fmac_f32_e32 v147, v146, v146
	v_fmac_f32_e32 v145, v144, v144
	v_add_f32_e32 v144, v147, v145
	v_mul_f32_e32 v145, v199, v199
	v_mul_f32_e32 v143, v143, v143
	v_fmac_f32_e32 v145, v198, v198
	v_fmac_f32_e32 v143, v142, v142
	v_add_f32_e32 v142, v145, v143
	v_add_f32_e32 v142, v144, v142
	v_mov_b32_e32 v143, v142
	s_nop 1
	v_permlane16_swap_b32_e32 v143, v142
	s_waitcnt lgkmcnt(0)
	v_add_f32_e32 v142, v142, v143
	v_mov_b32_e32 v143, v142
	s_nop 1
	v_permlane32_swap_b32_e32 v143, v142
	s_and_saveexec_b64 s[0:1], s[6:7]
	s_cbranch_execz .LBB0_510
	s_waitcnt lgkmcnt(0)
	v_add_f32_e32 v142, v142, v143
	ds_write_b32 v234, v142 offset:16

; __device__ __forceinline__ void convert_rows(const float* X, bf16_t* out, float* rsq, int gw, int ngw, int lane) {
;     for (int m = gw; m < M; m += ngw) {
;         const f32x4* xr = (const f32x4*)(X + (size_t)m * DM) + lane;
;         f32x4 v[8]; float s = 0.f;
; #pragma unroll
;         for (int j = 0; j < 8; ++j) { v[j] = xr[64 * j]; s += (v[j].x * v[j].x + v[j].y * v[j].y) + (v[j].z * v[j].z + v[j].w * v[j].w); }
;         s = wave_sum(s); if (lane == 0) rsq[m] = s;
.LBB0_569:
	global_load_dwordx4 v[30:33], v[34:35], off offset:-4096
	global_load_dwordx4 v[2:5], v[34:35], off offset:-3072
	global_load_dwordx4 v[6:9], v[34:35], off offset:-2048
	global_load_dwordx4 v[10:13], v[34:35], off offset:-1024
	global_load_dwordx4 v[14:17], v[34:35], off
	global_load_dwordx4 v[18:21], v[34:35], off offset:1024
	global_load_dwordx4 v[22:25], v[34:35], off offset:2048
	global_load_dwordx4 v[26:29], v[34:35], off offset:3072
	s_waitcnt vmcnt(0)
	v_mul_f32_e32 v1, v31, v31
	v_mul_f32_e32 v44, v33, v33
	v_mul_f32_e32 v45, v3, v3
	v_mul_f32_e32 v46, v5, v5
	v_mul_f32_e32 v47, v7, v7
	v_mul_f32_e32 v48, v9, v9
	v_fmac_f32_e32 v1, v30, v30
	v_fmac_f32_e32 v44, v32, v32
	v_fmac_f32_e32 v45, v2, v2
	v_fmac_f32_e32 v46, v4, v4
	v_mul_f32_e32 v49, v11, v11
	v_mul_f32_e32 v50, v13, v13
	v_fmac_f32_e32 v47, v6, v6
	v_fmac_f32_e32 v48, v8, v8
	v_add_f32_e32 v1, v1, v44
	v_add_f32_e32 v44, v45, v46
	v_mul_f32_e32 v51, v15, v15
	v_mul_f32_e32 v52, v17, v17
	v_fmac_f32_e32 v49, v10, v10
	v_fmac_f32_e32 v50, v12, v12
	v_add_f32_e32 v45, v47, v48
	v_add_f32_e32 v1, v1, v44
	v_mul_f32_e32 v53, v19, v19
	v_mul_f32_e32 v54, v21, v21
	v_fmac_f32_e32 v51, v14, v14
	v_fmac_f32_e32 v52, v16, v16
	v_add_f32_e32 v46, v49, v50
	v_add_f32_e32 v1, v1, v45
	v_mul_f32_e32 v55, v23, v23
	v_mul_f32_e32 v56, v25, v25
	v_fmac_f32_e32 v53, v18, v18
	v_fmac_f32_e32 v54, v20, v20
	v_add_f32_e32 v47, v51, v52
	v_add_f32_e32 v1, v1, v46
	v_mul_f32_e32 v57, v27, v27
	v_mul_f32_e32 v58, v29, v29
	v_fmac_f32_e32 v55, v22, v22
	v_fmac_f32_e32 v56, v24, v24
	v_add_f32_e32 v48, v53, v54
	v_add_f32_e32 v1, v1, v47
	v_fmac_f32_e32 v57, v26, v26
	v_fmac_f32_e32 v58, v28, v28
	v_add_f32_e32 v49, v55, v56
	v_add_f32_e32 v1, v1, v48
	v_add_f32_e32 v1, v1, v49
	v_add_f32_e32 v44, v57, v58
	v_add_f32_e32 v1, v1, v44
	s_nop 1
	v_mov_b32_dpp v44, v1 quad_perm:[1,0,3,2] row_mask:0xf bank_mask:0xf
	s_waitcnt lgkmcnt(0)
	v_add_f32_e32 v1, v1, v44
	s_nop 1
	v_mov_b32_dpp v44, v1 quad_perm:[2,3,0,1] row_mask:0xf bank_mask:0xf
	s_waitcnt lgkmcnt(0)
	v_add_f32_e32 v1, v1, v44
	s_nop 1
	v_mov_b32_dpp v44, v1 row_half_mirror row_mask:0xf bank_mask:0xf
	s_waitcnt lgkmcnt(0)
	v_add_f32_e32 v1, v1, v44
	s_nop 1
	v_mov_b32_dpp v44, v1 row_mirror row_mask:0xf bank_mask:0xf
	s_waitcnt lgkmcnt(0)
	v_add_f32_e32 v1, v1, v44
	v_mov_b32_e32 v44, v1
	s_nop 1
	v_permlane16_swap_b32_e32 v44, v1
	s_waitcnt lgkmcnt(0)
	v_add_f32_e32 v1, v1, v44
	v_mov_b32_e32 v44, v1
	s_nop 1
	v_permlane32_swap_b32_e32 v44, v1
	s_and_saveexec_b64 s[18:19], s[6:7]
	s_cbranch_execz .LBB0_568
	s_add_u32 s22, s0, s20
	s_waitcnt lgkmcnt(0)
	v_add_f32_e32 v1, v1, v44
	s_addc_u32 s23, s1, s21
	global_store_dword v197, v1, s[22:23]
	s_branch .LBB0_568
